# s_setprio 0 sunk below the closing K-loop phase barrier (20 sites)
# baseline (speedup 1.0000x reference)
; #define PG8_STAGE(bufoff, gbase, voff) do { _Pragma("unroll") for (int _i = 0; _i < 2; ++_i) \
;         __builtin_amdgcn_global_load_lds((const unsigned*)((const char*)(gbase) + (voff)[_i]), (PG8_LAS unsigned*)(lds + (bufoff) + ldsw + _i * 8192), 16, 0, 0); } while (0)
; #define PG8_LDA(dst, b, h) do { _Pragma("unroll") for (int m = 0; m < 4; ++m) _Pragma("unroll") for (int k = 0; k < 2; ++k) dst[m][k] = *(const PG8_LAS bf16x8*)(lds + PG8_SA(b, h) + aoff + m * 2048 + k * 1024); } while (0)
; #define PG8_LDB(dst, b, h) do { _Pragma("unroll") for (int n = 0; n < 2; ++n) _Pragma("unroll") for (int k = 0; k < 2; ++k) dst[n][k] = *(const PG8_LAS bf16x8*)(lds + PG8_SB(b, h) + boff + n * 2048 + k * 1024); } while (0)
; #define PG8_MMA(ai, bj, At, Bt) do { __builtin_amdgcn_s_setprio(1); _Pragma("unroll") for (int m = 0; m < 4; ++m) _Pragma("unroll") for (int n = 0; n < 2; ++n) _Pragma("unroll") for (int k = 0; k < 2; ++k) \
;         acc[ai][bj][m][n] = __builtin_amdgcn_mfma_f32_16x16x32_bf16(Bt[n][k], At[m][k], acc[ai][bj][m][n], 0, 0, 0); __builtin_amdgcn_s_setprio(0); } while (0)
; #define PG8_WAIT_V(n) asm volatile("s_waitcnt vmcnt(" #n ")" ::: "memory")
; #define PG8_WAIT_L(n) asm volatile("s_waitcnt lgkmcnt(" #n ")" ::: "memory")
; #define PG8_BAR __builtin_amdgcn_s_barrier()
; #define PG8_SCHED __builtin_amdgcn_sched_barrier(0)
; template <class Epi, class Sched, bool ALIGN_EPI = false, bool SP2 = false>
; __device__ __forceinline__ void gemm_phase(PG8_LAS unsigned char* lds, const Gemm g, const Sched& S, const Epi& E) {
;     ...
;             PG8_LDB(B0, 0, 0); PG8_LDB(B1, 0, 1); PG8_SCHED; PG8_LDA(At, 0, 0); PG8_STAGE(PG8_SA(1, 1), a1 + hstepA, voffA);
;             PG8_WAIT_V(8); PG8_WAIT_L(0); PG8_BAR; PG8_MMA(0, 0, At, B0); PG8_MMA(0, 1, At, B1); PG8_BAR; PG8_SCHED;
;             PG8_LDA(At, 0, 1); PG8_STAGE(PG8_SB(0, 0), b2, voffB); PG8_STAGE(PG8_SB(0, 1), b2 + hstepB, voffB); PG8_STAGE(PG8_SA(0, 0), a2, voffA);
;             PG8_WAIT_V(8); PG8_WAIT_L(0); PG8_BAR; PG8_MMA(1, 0, At, B0); PG8_MMA(1, 1, At, B1); PG8_BAR; PG8_SCHED;
.LBB0_157:
	v_add_u32_e32 v136, s2, v139
	ds_read_b128 v[186:189], v136
	ds_read_b128 v[190:193], v136 offset:1024
	ds_read_b128 v[194:197], v136 offset:2048
	ds_read_b128 v[198:201], v136 offset:3072
	v_add_u32_e32 v136, s3, v139
	ds_read_b128 v[202:205], v136
	ds_read_b128 v[206:209], v136 offset:1024
	ds_read_b128 v[210:213], v136 offset:2048
	ds_read_b128 v[214:217], v136 offset:3072
	s_add_u32 s38, s36, 0xfffc0080
	s_addc_u32 s39, s37, -1
	s_cmp_eq_u32 s45, 12
	s_cselect_b32 s41, s7, s39
	s_cselect_b32 s40, s29, s38
	s_cselect_b32 s39, s27, s44
	s_cselect_b32 s38, s42, s43
	v_lshl_add_u64 v[250:251], s[36:37], 0, v[178:179]
	s_add_i32 m0, s63, 0xc000
	ds_read_b128 v[218:221], v159
	ds_read_b128 v[222:225], v159 offset:1024
	ds_read_b128 v[226:229], v159 offset:2048
	ds_read_b128 v[230:233], v159 offset:3072
	ds_read_b128 v[234:237], v159 offset:4096
	ds_read_b128 v[238:241], v159 offset:5120
	ds_read_b128 v[242:245], v159 offset:6144
	ds_read_b128 v[246:249], v159 offset:7168
	global_load_lds_dwordx4 v[250:251], off
	v_lshl_add_u64 v[250:251], s[36:37], 0, v[180:181]
	s_add_i32 m0, s63, 0xe000
	s_nop 0
	global_load_lds_dwordx4 v[250:251], off
	s_waitcnt vmcnt(8) lgkmcnt(0)
	s_setprio 1
	s_barrier
	v_mfma_f32_16x16x32_bf16 v[124:127], v[186:189], v[218:221], v[124:127]
	v_mfma_f32_16x16x32_bf16 v[120:123], v[194:197], v[218:221], v[120:123]
	v_mfma_f32_16x16x32_bf16 v[108:111], v[186:189], v[226:229], v[108:111]
	v_mfma_f32_16x16x32_bf16 v[104:107], v[194:197], v[226:229], v[104:107]
	v_mfma_f32_16x16x32_bf16 v[92:95], v[186:189], v[234:237], v[92:95]
	v_mfma_f32_16x16x32_bf16 v[88:91], v[194:197], v[234:237], v[88:91]
	v_mfma_f32_16x16x32_bf16 v[76:79], v[186:189], v[242:245], v[76:79]
	v_mfma_f32_16x16x32_bf16 v[72:75], v[194:197], v[242:245], v[72:75]
	v_mfma_f32_16x16x32_bf16 v[124:127], v[190:193], v[222:225], v[124:127]
	v_mfma_f32_16x16x32_bf16 v[120:123], v[198:201], v[222:225], v[120:123]
	v_mfma_f32_16x16x32_bf16 v[108:111], v[190:193], v[230:233], v[108:111]
	v_mfma_f32_16x16x32_bf16 v[104:107], v[198:201], v[230:233], v[104:107]
	v_mfma_f32_16x16x32_bf16 v[92:95], v[190:193], v[238:241], v[92:95]
	v_mfma_f32_16x16x32_bf16 v[88:91], v[198:201], v[238:241], v[88:91]
	v_mfma_f32_16x16x32_bf16 v[76:79], v[190:193], v[246:249], v[76:79]
	v_mfma_f32_16x16x32_bf16 v[72:75], v[198:201], v[246:249], v[72:75]
	v_mfma_f32_16x16x32_bf16 v[116:119], v[202:205], v[218:221], v[116:119]
	v_mfma_f32_16x16x32_bf16 v[112:115], v[210:213], v[218:221], v[112:115]
	v_mfma_f32_16x16x32_bf16 v[100:103], v[202:205], v[226:229], v[100:103]
	v_mfma_f32_16x16x32_bf16 v[96:99], v[210:213], v[226:229], v[96:99]
	v_mfma_f32_16x16x32_bf16 v[84:87], v[202:205], v[234:237], v[84:87]
	v_mfma_f32_16x16x32_bf16 v[80:83], v[210:213], v[234:237], v[80:83]
	v_mfma_f32_16x16x32_bf16 v[68:71], v[202:205], v[242:245], v[68:71]
	v_mfma_f32_16x16x32_bf16 v[64:67], v[210:213], v[242:245], v[64:67]
	v_mfma_f32_16x16x32_bf16 v[116:119], v[206:209], v[222:225], v[116:119]
	v_mfma_f32_16x16x32_bf16 v[112:115], v[214:217], v[222:225], v[112:115]
	v_mfma_f32_16x16x32_bf16 v[100:103], v[206:209], v[230:233], v[100:103]
	v_mfma_f32_16x16x32_bf16 v[96:99], v[214:217], v[230:233], v[96:99]
	v_mfma_f32_16x16x32_bf16 v[84:87], v[206:209], v[238:241], v[84:87]
	v_mfma_f32_16x16x32_bf16 v[80:83], v[214:217], v[238:241], v[80:83]
	v_mfma_f32_16x16x32_bf16 v[68:71], v[206:209], v[246:249], v[68:71]
	v_mfma_f32_16x16x32_bf16 v[64:67], v[214:217], v[246:249], v[64:67]
	s_barrier
	s_setprio 0
	s_add_i32 s46, s2, s62
	v_lshl_add_u64 v[250:251], s[38:39], 0, v[130:131]
	s_mov_b32 m0, s46
	ds_read_b128 v[218:221], v159 offset:16384
	ds_read_b128 v[222:225], v159 offset:17408
	ds_read_b128 v[226:229], v159 offset:18432
	ds_read_b128 v[230:233], v159 offset:19456
	ds_read_b128 v[234:237], v159 offset:20480
	ds_read_b128 v[238:241], v159 offset:21504
	ds_read_b128 v[242:245], v159 offset:22528
	ds_read_b128 v[246:249], v159 offset:23552
	global_load_lds_dwordx4 v[250:251], off
	s_add_i32 m0, s46, 0x2000
	s_add_u32 s46, s38, 0x40000
	v_lshl_add_u64 v[252:253], s[38:39], 0, v[134:135]
	s_addc_u32 s47, s39, 0
	s_add_i32 s48, s3, s62
	global_load_lds_dwordx4 v[252:253], off
	v_lshl_add_u64 v[166:167], s[46:47], 0, v[130:131]
	s_mov_b32 m0, s48
	v_lshl_add_u64 v[168:169], s[40:41], 0, v[132:133]
	global_load_lds_dwordx4 v[166:167], off
	v_lshl_add_u64 v[166:167], s[46:47], 0, v[134:135]
	s_add_i32 m0, s48, 0x2000
	s_nop 0
	global_load_lds_dwordx4 v[166:167], off
	v_lshl_add_u64 v[166:167], s[40:41], 0, v[128:129]
	s_mov_b32 m0, s63
	s_nop 0
	global_load_lds_dwordx4 v[166:167], off
	s_mov_b32 m0, s64
	s_nop 0
	global_load_lds_dwordx4 v[168:169], off
	s_waitcnt vmcnt(8) lgkmcnt(0)
	s_setprio 1
	s_barrier
; #define PG8_STAGE(bufoff, gbase, voff) do { _Pragma("unroll") for (int _i = 0; _i < 2; ++_i) \
;         __builtin_amdgcn_global_load_lds((const unsigned*)((const char*)(gbase) + (voff)[_i]), (PG8_LAS unsigned*)(lds + (bufoff) + ldsw + _i * 8192), 16, 0, 0); } while (0)
; #define PG8_LDA(dst, b, h) do { _Pragma("unroll") for (int m = 0; m < 4; ++m) _Pragma("unroll") for (int k = 0; k < 2; ++k) dst[m][k] = *(const PG8_LAS bf16x8*)(lds + PG8_SA(b, h) + aoff + m * 2048 + k * 1024); } while (0)
; #define PG8_LDB(dst, b, h) do { _Pragma("unroll") for (int n = 0; n < 2; ++n) _Pragma("unroll") for (int k = 0; k < 2; ++k) dst[n][k] = *(const PG8_LAS bf16x8*)(lds + PG8_SB(b, h) + boff + n * 2048 + k * 1024); } while (0)
; #define PG8_MMA(ai, bj, At, Bt) do { __builtin_amdgcn_s_setprio(1); _Pragma("unroll") for (int m = 0; m < 4; ++m) _Pragma("unroll") for (int n = 0; n < 2; ++n) _Pragma("unroll") for (int k = 0; k < 2; ++k) \
;         acc[ai][bj][m][n] = __builtin_amdgcn_mfma_f32_16x16x32_bf16(Bt[n][k], At[m][k], acc[ai][bj][m][n], 0, 0, 0); __builtin_amdgcn_s_setprio(0); } while (0)
; #define PG8_WAIT_V(n) asm volatile("s_waitcnt vmcnt(" #n ")" ::: "memory")
; #define PG8_WAIT_L(n) asm volatile("s_waitcnt lgkmcnt(" #n ")" ::: "memory")
; #define PG8_BAR __builtin_amdgcn_s_barrier()
; #define PG8_SCHED __builtin_amdgcn_sched_barrier(0)
; template <class Epi, class Sched, bool ALIGN_EPI = false, bool SP2 = false>
; __device__ __forceinline__ void gemm_phase(PG8_LAS unsigned char* lds, const Gemm g, const Sched& S, const Epi& E) {
;     ...
;             PG8_WAIT_V(8); PG8_WAIT_L(0); PG8_BAR; PG8_MMA(1, 0, At, B0); PG8_MMA(1, 1, At, B1); PG8_BAR; PG8_SCHED;
;             PG8_LDB(B0, 1, 0); PG8_LDB(B1, 1, 1); PG8_SCHED; PG8_LDA(At, 1, 0); PG8_STAGE(PG8_SA(0, 1), a2 + hstepA, voffA);
;             PG8_WAIT_V(8); PG8_WAIT_L(0); PG8_BAR; PG8_MMA(0, 0, At, B0); PG8_MMA(0, 1, At, B1); PG8_BAR; PG8_SCHED;
	v_mfma_f32_16x16x32_bf16 v[60:63], v[186:189], v[218:221], v[60:63]
	v_mfma_f32_16x16x32_bf16 v[56:59], v[194:197], v[218:221], v[56:59]
	v_mfma_f32_16x16x32_bf16 v[44:47], v[186:189], v[226:229], v[44:47]
	v_mfma_f32_16x16x32_bf16 v[40:43], v[194:197], v[226:229], v[40:43]
	v_mfma_f32_16x16x32_bf16 v[28:31], v[186:189], v[234:237], v[28:31]
	v_mfma_f32_16x16x32_bf16 v[24:27], v[194:197], v[234:237], v[24:27]
	v_mfma_f32_16x16x32_bf16 v[12:15], v[186:189], v[242:245], v[12:15]
	v_mfma_f32_16x16x32_bf16 v[8:11], v[194:197], v[242:245], v[8:11]
	v_mfma_f32_16x16x32_bf16 v[60:63], v[190:193], v[222:225], v[60:63]
	v_mfma_f32_16x16x32_bf16 v[56:59], v[198:201], v[222:225], v[56:59]
	v_mfma_f32_16x16x32_bf16 v[44:47], v[190:193], v[230:233], v[44:47]
	v_mfma_f32_16x16x32_bf16 v[40:43], v[198:201], v[230:233], v[40:43]
	v_mfma_f32_16x16x32_bf16 v[28:31], v[190:193], v[238:241], v[28:31]
	v_mfma_f32_16x16x32_bf16 v[24:27], v[198:201], v[238:241], v[24:27]
	v_mfma_f32_16x16x32_bf16 v[12:15], v[190:193], v[246:249], v[12:15]
	v_mfma_f32_16x16x32_bf16 v[8:11], v[198:201], v[246:249], v[8:11]
	v_mfma_f32_16x16x32_bf16 v[52:55], v[202:205], v[218:221], v[52:55]
	v_mfma_f32_16x16x32_bf16 v[48:51], v[210:213], v[218:221], v[48:51]
	v_mfma_f32_16x16x32_bf16 v[36:39], v[202:205], v[226:229], v[36:39]
	v_mfma_f32_16x16x32_bf16 v[32:35], v[210:213], v[226:229], v[32:35]
	v_mfma_f32_16x16x32_bf16 v[20:23], v[202:205], v[234:237], v[20:23]
	v_mfma_f32_16x16x32_bf16 v[16:19], v[210:213], v[234:237], v[16:19]
	v_mfma_f32_16x16x32_bf16 v[4:7], v[202:205], v[242:245], v[4:7]
	v_mfma_f32_16x16x32_bf16 v[0:3], v[210:213], v[242:245], v[0:3]
	v_mfma_f32_16x16x32_bf16 v[52:55], v[206:209], v[222:225], v[52:55]
	v_mfma_f32_16x16x32_bf16 v[48:51], v[214:217], v[222:225], v[48:51]
	v_mfma_f32_16x16x32_bf16 v[36:39], v[206:209], v[230:233], v[36:39]
	v_mfma_f32_16x16x32_bf16 v[32:35], v[214:217], v[230:233], v[32:35]
	v_mfma_f32_16x16x32_bf16 v[20:23], v[206:209], v[238:241], v[20:23]
	v_mfma_f32_16x16x32_bf16 v[16:19], v[214:217], v[238:241], v[16:19]
	v_mfma_f32_16x16x32_bf16 v[4:7], v[206:209], v[246:249], v[4:7]
	v_mfma_f32_16x16x32_bf16 v[0:3], v[214:217], v[246:249], v[0:3]
	s_barrier
	s_setprio 0
	s_add_i32 s46, 0, 0x18000
	v_add_u32_e32 v136, s46, v139
	s_add_i32 s47, 0, 0x1c000
	ds_read_b128 v[186:189], v136
	ds_read_b128 v[190:193], v136 offset:1024
	ds_read_b128 v[194:197], v136 offset:2048
	ds_read_b128 v[198:201], v136 offset:3072
	v_add_u32_e32 v136, s47, v139
	ds_read_b128 v[202:205], v136
	ds_read_b128 v[206:209], v136 offset:1024
	ds_read_b128 v[210:213], v136 offset:2048
	ds_read_b128 v[214:217], v136 offset:3072
	s_add_u32 s40, s40, 0x40000
	s_addc_u32 s41, s41, 0
	s_mov_b32 m0, s65
	v_lshl_add_u64 v[170:171], s[40:41], 0, v[128:129]
	ds_read_b128 v[218:221], v159 offset:32768
	ds_read_b128 v[222:225], v159 offset:33792
	ds_read_b128 v[226:229], v159 offset:34816
	ds_read_b128 v[230:233], v159 offset:35840
	ds_read_b128 v[234:237], v159 offset:36864
	ds_read_b128 v[238:241], v159 offset:37888
	ds_read_b128 v[242:245], v159 offset:38912
	ds_read_b128 v[246:249], v159 offset:39936
	global_load_lds_dwordx4 v[170:171], off
	v_lshl_add_u64 v[170:171], s[40:41], 0, v[132:133]
	s_mov_b32 m0, s66
	s_nop 0
	global_load_lds_dwordx4 v[170:171], off
	s_waitcnt vmcnt(8) lgkmcnt(0)
	s_setprio 1
	s_barrier
	v_mfma_f32_16x16x32_bf16 v[124:127], v[186:189], v[218:221], v[124:127]
	v_mfma_f32_16x16x32_bf16 v[120:123], v[194:197], v[218:221], v[120:123]
	v_mfma_f32_16x16x32_bf16 v[108:111], v[186:189], v[226:229], v[108:111]
	v_mfma_f32_16x16x32_bf16 v[104:107], v[194:197], v[226:229], v[104:107]
	v_mfma_f32_16x16x32_bf16 v[92:95], v[186:189], v[234:237], v[92:95]
	v_mfma_f32_16x16x32_bf16 v[88:91], v[194:197], v[234:237], v[88:91]
	v_mfma_f32_16x16x32_bf16 v[76:79], v[186:189], v[242:245], v[76:79]
	v_mfma_f32_16x16x32_bf16 v[72:75], v[194:197], v[242:245], v[72:75]
	v_mfma_f32_16x16x32_bf16 v[124:127], v[190:193], v[222:225], v[124:127]
	v_mfma_f32_16x16x32_bf16 v[120:123], v[198:201], v[222:225], v[120:123]
	v_mfma_f32_16x16x32_bf16 v[108:111], v[190:193], v[230:233], v[108:111]
	v_mfma_f32_16x16x32_bf16 v[104:107], v[198:201], v[230:233], v[104:107]
	v_mfma_f32_16x16x32_bf16 v[92:95], v[190:193], v[238:241], v[92:95]
	v_mfma_f32_16x16x32_bf16 v[88:91], v[198:201], v[238:241], v[88:91]
	v_mfma_f32_16x16x32_bf16 v[76:79], v[190:193], v[246:249], v[76:79]
	v_mfma_f32_16x16x32_bf16 v[72:75], v[198:201], v[246:249], v[72:75]
	v_mfma_f32_16x16x32_bf16 v[116:119], v[202:205], v[218:221], v[116:119]
	v_mfma_f32_16x16x32_bf16 v[112:115], v[210:213], v[218:221], v[112:115]
	v_mfma_f32_16x16x32_bf16 v[100:103], v[202:205], v[226:229], v[100:103]
	v_mfma_f32_16x16x32_bf16 v[96:99], v[210:213], v[226:229], v[96:99]
	v_mfma_f32_16x16x32_bf16 v[84:87], v[202:205], v[234:237], v[84:87]
	v_mfma_f32_16x16x32_bf16 v[80:83], v[210:213], v[234:237], v[80:83]
	v_mfma_f32_16x16x32_bf16 v[68:71], v[202:205], v[242:245], v[68:71]
	v_mfma_f32_16x16x32_bf16 v[64:67], v[210:213], v[242:245], v[64:67]
	v_mfma_f32_16x16x32_bf16 v[116:119], v[206:209], v[222:225], v[116:119]
	v_mfma_f32_16x16x32_bf16 v[112:115], v[214:217], v[222:225], v[112:115]
	v_mfma_f32_16x16x32_bf16 v[100:103], v[206:209], v[230:233], v[100:103]
	v_mfma_f32_16x16x32_bf16 v[96:99], v[214:217], v[230:233], v[96:99]
	v_mfma_f32_16x16x32_bf16 v[84:87], v[206:209], v[238:241], v[84:87]
	v_mfma_f32_16x16x32_bf16 v[80:83], v[214:217], v[238:241], v[80:83]
	v_mfma_f32_16x16x32_bf16 v[68:71], v[206:209], v[246:249], v[68:71]
	v_mfma_f32_16x16x32_bf16 v[64:67], v[214:217], v[246:249], v[64:67]
	s_barrier
; #define PG8_STAGE(bufoff, gbase, voff) do { _Pragma("unroll") for (int _i = 0; _i < 2; ++_i) \
;         __builtin_amdgcn_global_load_lds((const unsigned*)((const char*)(gbase) + (voff)[_i]), (PG8_LAS unsigned*)(lds + (bufoff) + ldsw + _i * 8192), 16, 0, 0); } while (0)
; #define PG8_LDA(dst, b, h) do { _Pragma("unroll") for (int m = 0; m < 4; ++m) _Pragma("unroll") for (int k = 0; k < 2; ++k) dst[m][k] = *(const PG8_LAS bf16x8*)(lds + PG8_SA(b, h) + aoff + m * 2048 + k * 1024); } while (0)
; #define PG8_MMA(ai, bj, At, Bt) do { __builtin_amdgcn_s_setprio(1); _Pragma("unroll") for (int m = 0; m < 4; ++m) _Pragma("unroll") for (int n = 0; n < 2; ++n) _Pragma("unroll") for (int k = 0; k < 2; ++k) \
;         acc[ai][bj][m][n] = __builtin_amdgcn_mfma_f32_16x16x32_bf16(Bt[n][k], At[m][k], acc[ai][bj][m][n], 0, 0, 0); __builtin_amdgcn_s_setprio(0); } while (0)
; #define PG8_WAIT_V(n) asm volatile("s_waitcnt vmcnt(" #n ")" ::: "memory")
; #define PG8_WAIT_L(n) asm volatile("s_waitcnt lgkmcnt(" #n ")" ::: "memory")
; #define PG8_BAR __builtin_amdgcn_s_barrier()
; #define PG8_SCHED __builtin_amdgcn_sched_barrier(0)
; template <class Epi, class Sched, bool ALIGN_EPI = false, bool SP2 = false>
; __device__ __forceinline__ void gemm_phase(PG8_LAS unsigned char* lds, const Gemm g, const Sched& S, const Epi& E) {
;     ...
;             PG8_LDA(At, 1, 1); PG8_STAGE(PG8_SB(1, 0), b3, voffB); PG8_STAGE(PG8_SB(1, 1), b3 + hstepB, voffB); PG8_STAGE(PG8_SA(1, 0), a3, voffA);
;             PG8_WAIT_V(8); PG8_WAIT_L(0); PG8_BAR; PG8_MMA(1, 0, At, B0); PG8_MMA(1, 1, At, B1); PG8_BAR; PG8_SCHED;
;     ...
;         if constexpr (ALIGN_EPI) { if (wr == 0) PG8_BAR; }
	s_setprio 0
	s_add_i32 s40, s46, s62
	v_lshl_add_u64 v[170:171], v[250:251], 0, s[22:23]
	s_mov_b32 m0, s40
	ds_read_b128 v[218:221], v159 offset:49152
	ds_read_b128 v[222:225], v159 offset:50176
	ds_read_b128 v[226:229], v159 offset:51200
	ds_read_b128 v[230:233], v159 offset:52224
	ds_read_b128 v[234:237], v159 offset:53248
	ds_read_b128 v[238:241], v159 offset:54272
	ds_read_b128 v[242:245], v159 offset:55296
	ds_read_b128 v[246:249], v159 offset:56320
	global_load_lds_dwordx4 v[170:171], off
	s_add_i32 m0, s40, 0x2000
	s_add_u32 s38, s38, 0x40080
	v_lshl_add_u64 v[170:171], v[252:253], 0, s[22:23]
	s_addc_u32 s39, s39, 0
	s_add_i32 s40, s47, s62
	global_load_lds_dwordx4 v[170:171], off
	v_lshl_add_u64 v[170:171], s[38:39], 0, v[130:131]
	s_mov_b32 m0, s40
	v_lshl_add_u64 v[166:167], v[166:167], 0, s[22:23]
	global_load_lds_dwordx4 v[170:171], off
	v_lshl_add_u64 v[170:171], s[38:39], 0, v[134:135]
	s_add_i32 m0, s40, 0x2000
	s_nop 0
	global_load_lds_dwordx4 v[170:171], off
	s_mov_b32 m0, s93
	s_nop 0
	global_load_lds_dwordx4 v[166:167], off
	v_lshl_add_u64 v[166:167], v[168:169], 0, s[22:23]
	s_mov_b32 m0, s96
	s_nop 0
	global_load_lds_dwordx4 v[166:167], off
	s_waitcnt vmcnt(8) lgkmcnt(0)
	s_setprio 1
	s_barrier
	v_mfma_f32_16x16x32_bf16 v[60:63], v[186:189], v[218:221], v[60:63]
	v_mfma_f32_16x16x32_bf16 v[56:59], v[194:197], v[218:221], v[56:59]
	v_mfma_f32_16x16x32_bf16 v[44:47], v[186:189], v[226:229], v[44:47]
	v_mfma_f32_16x16x32_bf16 v[40:43], v[194:197], v[226:229], v[40:43]
	v_mfma_f32_16x16x32_bf16 v[28:31], v[186:189], v[234:237], v[28:31]
	v_mfma_f32_16x16x32_bf16 v[24:27], v[194:197], v[234:237], v[24:27]
	v_mfma_f32_16x16x32_bf16 v[12:15], v[186:189], v[242:245], v[12:15]
	v_mfma_f32_16x16x32_bf16 v[8:11], v[194:197], v[242:245], v[8:11]
	v_mfma_f32_16x16x32_bf16 v[60:63], v[190:193], v[222:225], v[60:63]
	v_mfma_f32_16x16x32_bf16 v[56:59], v[198:201], v[222:225], v[56:59]
	v_mfma_f32_16x16x32_bf16 v[44:47], v[190:193], v[230:233], v[44:47]
	v_mfma_f32_16x16x32_bf16 v[40:43], v[198:201], v[230:233], v[40:43]
	v_mfma_f32_16x16x32_bf16 v[28:31], v[190:193], v[238:241], v[28:31]
	v_mfma_f32_16x16x32_bf16 v[24:27], v[198:201], v[238:241], v[24:27]
	v_mfma_f32_16x16x32_bf16 v[12:15], v[190:193], v[246:249], v[12:15]
	v_mfma_f32_16x16x32_bf16 v[8:11], v[198:201], v[246:249], v[8:11]
	v_mfma_f32_16x16x32_bf16 v[52:55], v[202:205], v[218:221], v[52:55]
	v_mfma_f32_16x16x32_bf16 v[48:51], v[210:213], v[218:221], v[48:51]
	v_mfma_f32_16x16x32_bf16 v[36:39], v[202:205], v[226:229], v[36:39]
	v_mfma_f32_16x16x32_bf16 v[32:35], v[210:213], v[226:229], v[32:35]
	v_mfma_f32_16x16x32_bf16 v[20:23], v[202:205], v[234:237], v[20:23]
	v_mfma_f32_16x16x32_bf16 v[16:19], v[210:213], v[234:237], v[16:19]
	v_mfma_f32_16x16x32_bf16 v[4:7], v[202:205], v[242:245], v[4:7]
	v_mfma_f32_16x16x32_bf16 v[0:3], v[210:213], v[242:245], v[0:3]
	v_mfma_f32_16x16x32_bf16 v[52:55], v[206:209], v[222:225], v[52:55]
	v_mfma_f32_16x16x32_bf16 v[48:51], v[214:217], v[222:225], v[48:51]
	v_mfma_f32_16x16x32_bf16 v[36:39], v[206:209], v[230:233], v[36:39]
	v_mfma_f32_16x16x32_bf16 v[32:35], v[214:217], v[230:233], v[32:35]
	v_mfma_f32_16x16x32_bf16 v[20:23], v[206:209], v[238:241], v[20:23]
	v_mfma_f32_16x16x32_bf16 v[16:19], v[214:217], v[238:241], v[16:19]
	v_mfma_f32_16x16x32_bf16 v[4:7], v[206:209], v[246:249], v[4:7]
	v_mfma_f32_16x16x32_bf16 v[0:3], v[214:217], v[246:249], v[0:3]
	s_barrier
	s_setprio 0
	s_add_i32 s45, s45, 2
	s_add_u32 s36, s36, 0x100
	s_addc_u32 s37, s37, 0
	s_add_u32 s43, s43, 0x100
	s_addc_u32 s44, s44, 0
	s_cmp_gt_u32 s45, 13
	s_cbranch_scc0 .LBB0_157
	s_and_b64 vcc, exec, s[24:25]
	s_cbranch_vccz .LBB0_160
	s_barrier

; #define PG8_STAGE(bufoff, gbase, voff) do { _Pragma("unroll") for (int _i = 0; _i < 2; ++_i) \
;         __builtin_amdgcn_global_load_lds((const unsigned*)((const char*)(gbase) + (voff)[_i]), (PG8_LAS unsigned*)(lds + (bufoff) + ldsw + _i * 8192), 16, 0, 0); } while (0)
; #define PG8_LDA(dst, b, h) do { _Pragma("unroll") for (int m = 0; m < 4; ++m) _Pragma("unroll") for (int k = 0; k < 2; ++k) dst[m][k] = *(const PG8_LAS bf16x8*)(lds + PG8_SA(b, h) + aoff + m * 2048 + k * 1024); } while (0)
; #define PG8_LDB(dst, b, h) do { _Pragma("unroll") for (int n = 0; n < 2; ++n) _Pragma("unroll") for (int k = 0; k < 2; ++k) dst[n][k] = *(const PG8_LAS bf16x8*)(lds + PG8_SB(b, h) + boff + n * 2048 + k * 1024); } while (0)
; #define PG8_MMA(ai, bj, At, Bt) do { __builtin_amdgcn_s_setprio(1); _Pragma("unroll") for (int m = 0; m < 4; ++m) _Pragma("unroll") for (int n = 0; n < 2; ++n) _Pragma("unroll") for (int k = 0; k < 2; ++k) \
;         acc[ai][bj][m][n] = __builtin_amdgcn_mfma_f32_16x16x32_bf16(Bt[n][k], At[m][k], acc[ai][bj][m][n], 0, 0, 0); __builtin_amdgcn_s_setprio(0); } while (0)
; #define PG8_WAIT_V(n) asm volatile("s_waitcnt vmcnt(" #n ")" ::: "memory")
; #define PG8_WAIT_L(n) asm volatile("s_waitcnt lgkmcnt(" #n ")" ::: "memory")
; #define PG8_BAR __builtin_amdgcn_s_barrier()
; #define PG8_SCHED __builtin_amdgcn_sched_barrier(0)
; template <class Epi, class Sched, bool ALIGN_EPI = false, bool SP2 = false>
; __device__ __forceinline__ void gemm_phase(PG8_LAS unsigned char* lds, const Gemm g, const Sched& S, const Epi& E) {
;     ...
;             PG8_LDB(B0, 0, 0); PG8_LDB(B1, 0, 1); PG8_SCHED; PG8_LDA(At, 0, 0); PG8_STAGE(PG8_SA(1, 1), a1 + hstepA, voffA);
;             PG8_WAIT_V(8); PG8_WAIT_L(0); PG8_BAR; PG8_MMA(0, 0, At, B0); PG8_MMA(0, 1, At, B1); PG8_BAR; PG8_SCHED;
;             PG8_LDA(At, 0, 1); PG8_STAGE(PG8_SB(0, 0), b2, voffB); PG8_STAGE(PG8_SB(0, 1), b2 + hstepB, voffB); PG8_STAGE(PG8_SA(0, 0), a2, voffA);
.LBB0_470:
	ds_read_b128 v[158:161], v155
	ds_read_b128 v[162:165], v155 offset:1024
	ds_read_b128 v[166:169], v155 offset:2048
	ds_read_b128 v[170:173], v155 offset:3072
	ds_read_b128 v[174:177], v156
	ds_read_b128 v[178:181], v156 offset:1024
	ds_read_b128 v[186:189], v156 offset:2048
	ds_read_b128 v[190:193], v156 offset:3072
	s_add_u32 s12, s0, 0xfffc0080
	s_addc_u32 s13, s1, -1
	s_cmp_eq_u32 s44, 4
	s_cselect_b32 s17, s38, s13
	s_cselect_b32 s16, s39, s12
	s_cselect_b32 s13, s40, s43
	s_cselect_b32 s12, s41, s42
	v_lshl_add_u64 v[182:183], s[0:1], 0, v[140:141]
	s_add_i32 m0, s22, 0xc000
	ds_read_b128 v[194:197], v157
	ds_read_b128 v[198:201], v157 offset:1024
	ds_read_b128 v[202:205], v157 offset:2048
	ds_read_b128 v[206:209], v157 offset:3072
	ds_read_b128 v[210:213], v157 offset:4096
	ds_read_b128 v[214:217], v157 offset:5120
	ds_read_b128 v[218:221], v157 offset:6144
	ds_read_b128 v[222:225], v157 offset:7168
	global_load_lds_dwordx4 v[182:183], off
	v_lshl_add_u64 v[182:183], s[0:1], 0, v[142:143]
	s_add_i32 m0, s22, 0xe000
	s_nop 0
	global_load_lds_dwordx4 v[182:183], off
	s_waitcnt vmcnt(8) lgkmcnt(0)
	s_setprio 1
	s_barrier
	v_mfma_f32_16x16x32_bf16 v[124:127], v[158:161], v[194:197], v[124:127]
	v_mfma_f32_16x16x32_bf16 v[120:123], v[166:169], v[194:197], v[120:123]
	v_mfma_f32_16x16x32_bf16 v[116:119], v[158:161], v[202:205], v[116:119]
	v_mfma_f32_16x16x32_bf16 v[112:115], v[166:169], v[202:205], v[112:115]
	v_mfma_f32_16x16x32_bf16 v[108:111], v[158:161], v[210:213], v[108:111]
	v_mfma_f32_16x16x32_bf16 v[100:103], v[166:169], v[210:213], v[100:103]
	v_mfma_f32_16x16x32_bf16 v[92:95], v[158:161], v[218:221], v[92:95]
	v_mfma_f32_16x16x32_bf16 v[84:87], v[166:169], v[218:221], v[84:87]
	v_mfma_f32_16x16x32_bf16 v[124:127], v[162:165], v[198:201], v[124:127]
	v_mfma_f32_16x16x32_bf16 v[120:123], v[170:173], v[198:201], v[120:123]
	v_mfma_f32_16x16x32_bf16 v[116:119], v[162:165], v[206:209], v[116:119]
	v_mfma_f32_16x16x32_bf16 v[112:115], v[170:173], v[206:209], v[112:115]
	v_mfma_f32_16x16x32_bf16 v[108:111], v[162:165], v[214:217], v[108:111]
	v_mfma_f32_16x16x32_bf16 v[100:103], v[170:173], v[214:217], v[100:103]
	v_mfma_f32_16x16x32_bf16 v[92:95], v[162:165], v[222:225], v[92:95]
	v_mfma_f32_16x16x32_bf16 v[84:87], v[170:173], v[222:225], v[84:87]
	v_mfma_f32_16x16x32_bf16 v[104:107], v[174:177], v[194:197], v[104:107]
	v_mfma_f32_16x16x32_bf16 v[96:99], v[186:189], v[194:197], v[96:99]
	v_mfma_f32_16x16x32_bf16 v[88:91], v[174:177], v[202:205], v[88:91]
	v_mfma_f32_16x16x32_bf16 v[80:83], v[186:189], v[202:205], v[80:83]
	v_mfma_f32_16x16x32_bf16 v[76:79], v[174:177], v[210:213], v[76:79]
	v_mfma_f32_16x16x32_bf16 v[72:75], v[186:189], v[210:213], v[72:75]
	v_mfma_f32_16x16x32_bf16 v[68:71], v[174:177], v[218:221], v[68:71]
	v_mfma_f32_16x16x32_bf16 v[64:67], v[186:189], v[218:221], v[64:67]
	v_mfma_f32_16x16x32_bf16 v[104:107], v[178:181], v[198:201], v[104:107]
	v_mfma_f32_16x16x32_bf16 v[96:99], v[190:193], v[198:201], v[96:99]
	v_mfma_f32_16x16x32_bf16 v[88:91], v[178:181], v[206:209], v[88:91]
	v_mfma_f32_16x16x32_bf16 v[80:83], v[190:193], v[206:209], v[80:83]
	v_mfma_f32_16x16x32_bf16 v[76:79], v[178:181], v[214:217], v[76:79]
	v_mfma_f32_16x16x32_bf16 v[72:75], v[190:193], v[214:217], v[72:75]
	v_mfma_f32_16x16x32_bf16 v[68:71], v[178:181], v[222:225], v[68:71]
	v_mfma_f32_16x16x32_bf16 v[64:67], v[190:193], v[222:225], v[64:67]
	s_barrier
	s_setprio 0
	s_add_i32 s45, s33, s15
	v_lshl_add_u64 v[182:183], s[12:13], 0, v[132:133]
	s_mov_b32 m0, s45
	ds_read_b128 v[194:197], v157 offset:16384
	ds_read_b128 v[198:201], v157 offset:17408
	ds_read_b128 v[202:205], v157 offset:18432
	ds_read_b128 v[206:209], v157 offset:19456
	ds_read_b128 v[210:213], v157 offset:20480
	ds_read_b128 v[214:217], v157 offset:21504
	ds_read_b128 v[218:221], v157 offset:22528
	ds_read_b128 v[222:225], v157 offset:23552
	global_load_lds_dwordx4 v[182:183], off
	s_add_i32 m0, s45, 0x2000
	s_add_u32 s46, s12, 0x80000
	v_lshl_add_u64 v[226:227], s[12:13], 0, v[128:129]
	s_addc_u32 s47, s13, 0
	s_add_i32 s45, s34, s15
	global_load_lds_dwordx4 v[226:227], off
	v_lshl_add_u64 v[228:229], s[46:47], 0, v[132:133]
	s_mov_b32 m0, s45
	v_lshl_add_u64 v[230:231], s[16:17], 0, v[130:131]
	global_load_lds_dwordx4 v[228:229], off
	v_lshl_add_u64 v[228:229], s[46:47], 0, v[128:129]
	s_add_i32 m0, s45, 0x2000
	s_nop 0
	global_load_lds_dwordx4 v[228:229], off
	v_lshl_add_u64 v[228:229], s[16:17], 0, v[134:135]
	s_mov_b32 m0, s22
	s_nop 0
	global_load_lds_dwordx4 v[228:229], off
	s_mov_b32 m0, s25
	s_nop 0
	global_load_lds_dwordx4 v[230:231], off
	s_waitcnt vmcnt(8) lgkmcnt(0)
	s_setprio 1
	s_barrier
; #define PG8_STAGE(bufoff, gbase, voff) do { _Pragma("unroll") for (int _i = 0; _i < 2; ++_i) \
;         __builtin_amdgcn_global_load_lds((const unsigned*)((const char*)(gbase) + (voff)[_i]), (PG8_LAS unsigned*)(lds + (bufoff) + ldsw + _i * 8192), 16, 0, 0); } while (0)
; #define PG8_LDA(dst, b, h) do { _Pragma("unroll") for (int m = 0; m < 4; ++m) _Pragma("unroll") for (int k = 0; k < 2; ++k) dst[m][k] = *(const PG8_LAS bf16x8*)(lds + PG8_SA(b, h) + aoff + m * 2048 + k * 1024); } while (0)
; #define PG8_LDB(dst, b, h) do { _Pragma("unroll") for (int n = 0; n < 2; ++n) _Pragma("unroll") for (int k = 0; k < 2; ++k) dst[n][k] = *(const PG8_LAS bf16x8*)(lds + PG8_SB(b, h) + boff + n * 2048 + k * 1024); } while (0)
; #define PG8_MMA(ai, bj, At, Bt) do { __builtin_amdgcn_s_setprio(1); _Pragma("unroll") for (int m = 0; m < 4; ++m) _Pragma("unroll") for (int n = 0; n < 2; ++n) _Pragma("unroll") for (int k = 0; k < 2; ++k) \
;         acc[ai][bj][m][n] = __builtin_amdgcn_mfma_f32_16x16x32_bf16(Bt[n][k], At[m][k], acc[ai][bj][m][n], 0, 0, 0); __builtin_amdgcn_s_setprio(0); } while (0)
; #define PG8_WAIT_V(n) asm volatile("s_waitcnt vmcnt(" #n ")" ::: "memory")
; #define PG8_WAIT_L(n) asm volatile("s_waitcnt lgkmcnt(" #n ")" ::: "memory")
; #define PG8_BAR __builtin_amdgcn_s_barrier()
; #define PG8_SCHED __builtin_amdgcn_sched_barrier(0)
; template <class Epi, class Sched, bool ALIGN_EPI = false, bool SP2 = false>
; __device__ __forceinline__ void gemm_phase(PG8_LAS unsigned char* lds, const Gemm g, const Sched& S, const Epi& E) {
;     ...
;             PG8_WAIT_V(8); PG8_WAIT_L(0); PG8_BAR; PG8_MMA(1, 0, At, B0); PG8_MMA(1, 1, At, B1); PG8_BAR; PG8_SCHED;
;             PG8_LDB(B0, 1, 0); PG8_LDB(B1, 1, 1); PG8_SCHED; PG8_LDA(At, 1, 0); PG8_STAGE(PG8_SA(0, 1), a2 + hstepA, voffA);
;             PG8_WAIT_V(8); PG8_WAIT_L(0); PG8_BAR; PG8_MMA(0, 0, At, B0); PG8_MMA(0, 1, At, B1); PG8_BAR; PG8_SCHED;
	v_mfma_f32_16x16x32_bf16 v[60:63], v[158:161], v[194:197], v[60:63]
	v_mfma_f32_16x16x32_bf16 v[56:59], v[166:169], v[194:197], v[56:59]
	v_mfma_f32_16x16x32_bf16 v[52:55], v[158:161], v[202:205], v[52:55]
	v_mfma_f32_16x16x32_bf16 v[48:51], v[166:169], v[202:205], v[48:51]
	v_mfma_f32_16x16x32_bf16 v[44:47], v[158:161], v[210:213], v[44:47]
	v_mfma_f32_16x16x32_bf16 v[36:39], v[166:169], v[210:213], v[36:39]
	v_mfma_f32_16x16x32_bf16 v[28:31], v[158:161], v[218:221], v[28:31]
	v_mfma_f32_16x16x32_bf16 v[20:23], v[166:169], v[218:221], v[20:23]
	v_mfma_f32_16x16x32_bf16 v[60:63], v[162:165], v[198:201], v[60:63]
	v_mfma_f32_16x16x32_bf16 v[56:59], v[170:173], v[198:201], v[56:59]
	v_mfma_f32_16x16x32_bf16 v[52:55], v[162:165], v[206:209], v[52:55]
	v_mfma_f32_16x16x32_bf16 v[48:51], v[170:173], v[206:209], v[48:51]
	v_mfma_f32_16x16x32_bf16 v[44:47], v[162:165], v[214:217], v[44:47]
	v_mfma_f32_16x16x32_bf16 v[36:39], v[170:173], v[214:217], v[36:39]
	v_mfma_f32_16x16x32_bf16 v[28:31], v[162:165], v[222:225], v[28:31]
	v_mfma_f32_16x16x32_bf16 v[20:23], v[170:173], v[222:225], v[20:23]
	v_mfma_f32_16x16x32_bf16 v[40:43], v[174:177], v[194:197], v[40:43]
	v_mfma_f32_16x16x32_bf16 v[32:35], v[186:189], v[194:197], v[32:35]
	v_mfma_f32_16x16x32_bf16 v[24:27], v[174:177], v[202:205], v[24:27]
	v_mfma_f32_16x16x32_bf16 v[16:19], v[186:189], v[202:205], v[16:19]
	v_mfma_f32_16x16x32_bf16 v[12:15], v[174:177], v[210:213], v[12:15]
	v_mfma_f32_16x16x32_bf16 v[8:11], v[186:189], v[210:213], v[8:11]
	v_mfma_f32_16x16x32_bf16 v[4:7], v[174:177], v[218:221], v[4:7]
	v_mfma_f32_16x16x32_bf16 v[0:3], v[186:189], v[218:221], v[0:3]
	v_mfma_f32_16x16x32_bf16 v[40:43], v[178:181], v[198:201], v[40:43]
	v_mfma_f32_16x16x32_bf16 v[32:35], v[190:193], v[198:201], v[32:35]
	v_mfma_f32_16x16x32_bf16 v[24:27], v[178:181], v[206:209], v[24:27]
	v_mfma_f32_16x16x32_bf16 v[16:19], v[190:193], v[206:209], v[16:19]
	v_mfma_f32_16x16x32_bf16 v[12:15], v[178:181], v[214:217], v[12:15]
	v_mfma_f32_16x16x32_bf16 v[8:11], v[190:193], v[214:217], v[8:11]
	v_mfma_f32_16x16x32_bf16 v[4:7], v[178:181], v[222:225], v[4:7]
	v_mfma_f32_16x16x32_bf16 v[0:3], v[190:193], v[222:225], v[0:3]
	s_barrier
	s_setprio 0
	s_add_i32 s45, 0, 0x18000
	v_add_u32_e32 v136, s45, v150
	s_add_i32 s46, 0, 0x1c000
	ds_read_b128 v[158:161], v136
	ds_read_b128 v[162:165], v136 offset:1024
	ds_read_b128 v[166:169], v136 offset:2048
	ds_read_b128 v[170:173], v136 offset:3072
	v_add_u32_e32 v136, s46, v150
	ds_read_b128 v[174:177], v136
	ds_read_b128 v[178:181], v136 offset:1024
	ds_read_b128 v[186:189], v136 offset:2048
	ds_read_b128 v[190:193], v136 offset:3072
	s_add_u32 s16, s16, 0x40000
	s_addc_u32 s17, s17, 0
	s_mov_b32 m0, s26
	v_lshl_add_u64 v[232:233], s[16:17], 0, v[134:135]
	ds_read_b128 v[194:197], v157 offset:32768
	ds_read_b128 v[198:201], v157 offset:33792
	ds_read_b128 v[202:205], v157 offset:34816
	ds_read_b128 v[206:209], v157 offset:35840
	ds_read_b128 v[210:213], v157 offset:36864
	ds_read_b128 v[214:217], v157 offset:37888
	ds_read_b128 v[218:221], v157 offset:38912
	ds_read_b128 v[222:225], v157 offset:39936
	global_load_lds_dwordx4 v[232:233], off
	v_lshl_add_u64 v[232:233], s[16:17], 0, v[130:131]
	s_mov_b32 m0, s27
	s_nop 0
	global_load_lds_dwordx4 v[232:233], off
	s_waitcnt vmcnt(8) lgkmcnt(0)
	s_setprio 1
	s_barrier
	v_mfma_f32_16x16x32_bf16 v[124:127], v[158:161], v[194:197], v[124:127]
	v_mfma_f32_16x16x32_bf16 v[120:123], v[166:169], v[194:197], v[120:123]
	v_mfma_f32_16x16x32_bf16 v[116:119], v[158:161], v[202:205], v[116:119]
	v_mfma_f32_16x16x32_bf16 v[112:115], v[166:169], v[202:205], v[112:115]
	v_mfma_f32_16x16x32_bf16 v[108:111], v[158:161], v[210:213], v[108:111]
	v_mfma_f32_16x16x32_bf16 v[100:103], v[166:169], v[210:213], v[100:103]
	v_mfma_f32_16x16x32_bf16 v[92:95], v[158:161], v[218:221], v[92:95]
	v_mfma_f32_16x16x32_bf16 v[84:87], v[166:169], v[218:221], v[84:87]
	v_mfma_f32_16x16x32_bf16 v[124:127], v[162:165], v[198:201], v[124:127]
	v_mfma_f32_16x16x32_bf16 v[120:123], v[170:173], v[198:201], v[120:123]
	v_mfma_f32_16x16x32_bf16 v[116:119], v[162:165], v[206:209], v[116:119]
	v_mfma_f32_16x16x32_bf16 v[112:115], v[170:173], v[206:209], v[112:115]
	v_mfma_f32_16x16x32_bf16 v[108:111], v[162:165], v[214:217], v[108:111]
	v_mfma_f32_16x16x32_bf16 v[100:103], v[170:173], v[214:217], v[100:103]
	v_mfma_f32_16x16x32_bf16 v[92:95], v[162:165], v[222:225], v[92:95]
	v_mfma_f32_16x16x32_bf16 v[84:87], v[170:173], v[222:225], v[84:87]
	v_mfma_f32_16x16x32_bf16 v[104:107], v[174:177], v[194:197], v[104:107]
	v_mfma_f32_16x16x32_bf16 v[96:99], v[186:189], v[194:197], v[96:99]
	v_mfma_f32_16x16x32_bf16 v[88:91], v[174:177], v[202:205], v[88:91]
	v_mfma_f32_16x16x32_bf16 v[80:83], v[186:189], v[202:205], v[80:83]
	v_mfma_f32_16x16x32_bf16 v[76:79], v[174:177], v[210:213], v[76:79]
	v_mfma_f32_16x16x32_bf16 v[72:75], v[186:189], v[210:213], v[72:75]
	v_mfma_f32_16x16x32_bf16 v[68:71], v[174:177], v[218:221], v[68:71]
	v_mfma_f32_16x16x32_bf16 v[64:67], v[186:189], v[218:221], v[64:67]
	v_mfma_f32_16x16x32_bf16 v[104:107], v[178:181], v[198:201], v[104:107]
	v_mfma_f32_16x16x32_bf16 v[96:99], v[190:193], v[198:201], v[96:99]
	v_mfma_f32_16x16x32_bf16 v[88:91], v[178:181], v[206:209], v[88:91]
	v_mfma_f32_16x16x32_bf16 v[80:83], v[190:193], v[206:209], v[80:83]
	v_mfma_f32_16x16x32_bf16 v[76:79], v[178:181], v[214:217], v[76:79]
	v_mfma_f32_16x16x32_bf16 v[72:75], v[190:193], v[214:217], v[72:75]
	v_mfma_f32_16x16x32_bf16 v[68:71], v[178:181], v[222:225], v[68:71]
	v_mfma_f32_16x16x32_bf16 v[64:67], v[190:193], v[222:225], v[64:67]
	s_barrier
; #define PG8_STAGE(bufoff, gbase, voff) do { _Pragma("unroll") for (int _i = 0; _i < 2; ++_i) \
;         __builtin_amdgcn_global_load_lds((const unsigned*)((const char*)(gbase) + (voff)[_i]), (PG8_LAS unsigned*)(lds + (bufoff) + ldsw + _i * 8192), 16, 0, 0); } while (0)
; #define PG8_LDA(dst, b, h) do { _Pragma("unroll") for (int m = 0; m < 4; ++m) _Pragma("unroll") for (int k = 0; k < 2; ++k) dst[m][k] = *(const PG8_LAS bf16x8*)(lds + PG8_SA(b, h) + aoff + m * 2048 + k * 1024); } while (0)
; #define PG8_MMA(ai, bj, At, Bt) do { __builtin_amdgcn_s_setprio(1); _Pragma("unroll") for (int m = 0; m < 4; ++m) _Pragma("unroll") for (int n = 0; n < 2; ++n) _Pragma("unroll") for (int k = 0; k < 2; ++k) \
;         acc[ai][bj][m][n] = __builtin_amdgcn_mfma_f32_16x16x32_bf16(Bt[n][k], At[m][k], acc[ai][bj][m][n], 0, 0, 0); __builtin_amdgcn_s_setprio(0); } while (0)
; #define PG8_WAIT_V(n) asm volatile("s_waitcnt vmcnt(" #n ")" ::: "memory")
; #define PG8_WAIT_L(n) asm volatile("s_waitcnt lgkmcnt(" #n ")" ::: "memory")
; #define PG8_BAR __builtin_amdgcn_s_barrier()
; #define PG8_SCHED __builtin_amdgcn_sched_barrier(0)
; template <class Epi, class Sched, bool ALIGN_EPI = false, bool SP2 = false>
; __device__ __forceinline__ void gemm_phase(PG8_LAS unsigned char* lds, const Gemm g, const Sched& S, const Epi& E) {
;     ...
;             PG8_LDA(At, 1, 1); PG8_STAGE(PG8_SB(1, 0), b3, voffB); PG8_STAGE(PG8_SB(1, 1), b3 + hstepB, voffB); PG8_STAGE(PG8_SA(1, 0), a3, voffA);
;             PG8_WAIT_V(8); PG8_WAIT_L(0); PG8_BAR; PG8_MMA(1, 0, At, B0); PG8_MMA(1, 1, At, B1); PG8_BAR; PG8_SCHED;
;     __device__ __forceinline__ void operator()(const f32x4 (&acc)[2][2][4][2], const pg8::Unit& u, int wr, int wc, int fr, int fq) const {
;         float* base = part + (size_t)(u.koff >> 10) * 8192 * 256;
; #pragma unroll
;         for (int ai = 0; ai < 2; ++ai)
; #pragma unroll
;             for (int m = 0; m < 4; ++m) {
;                 const int row = u.pm * 256 + ai * 128 + wr * 64 + m * 16 + fr;
; #pragma unroll
;                 for (int bj = 0; bj < 2; ++bj) {
;                     float* p = base + (size_t)row * 256 + 128 * bj + 32 * wc + 8 * fq;
;                     *(f32x4*)p = acc[ai][bj][m][0]; *(f32x4*)(p + 4) = acc[ai][bj][m][1];
;                 }
;             }
	s_setprio 0
	s_add_i32 s16, s45, s15
	v_lshl_add_u64 v[182:183], v[182:183], 0, s[10:11]
	s_mov_b32 m0, s16
	ds_read_b128 v[194:197], v157 offset:49152
	ds_read_b128 v[198:201], v157 offset:50176
	ds_read_b128 v[202:205], v157 offset:51200
	ds_read_b128 v[206:209], v157 offset:52224
	ds_read_b128 v[210:213], v157 offset:53248
	ds_read_b128 v[214:217], v157 offset:54272
	ds_read_b128 v[218:221], v157 offset:55296
	ds_read_b128 v[222:225], v157 offset:56320
	global_load_lds_dwordx4 v[182:183], off
	s_add_i32 m0, s16, 0x2000
	s_add_u32 s12, s12, 0x80080
	v_lshl_add_u64 v[182:183], v[226:227], 0, s[10:11]
	s_addc_u32 s13, s13, 0
	s_add_i32 s16, s46, s15
	global_load_lds_dwordx4 v[182:183], off
	v_lshl_add_u64 v[182:183], s[12:13], 0, v[132:133]
	s_mov_b32 m0, s16
	s_nop 0
	global_load_lds_dwordx4 v[182:183], off
	v_lshl_add_u64 v[182:183], s[12:13], 0, v[128:129]
	s_add_i32 m0, s16, 0x2000
	s_nop 0
	global_load_lds_dwordx4 v[182:183], off
	v_lshl_add_u64 v[182:183], v[228:229], 0, s[10:11]
	s_mov_b32 m0, s30
	s_nop 0
	global_load_lds_dwordx4 v[182:183], off
	v_lshl_add_u64 v[182:183], v[230:231], 0, s[10:11]
	s_mov_b32 m0, s31
	s_nop 0
	global_load_lds_dwordx4 v[182:183], off
	s_waitcnt vmcnt(8) lgkmcnt(0)
	s_setprio 1
	s_barrier
	v_mfma_f32_16x16x32_bf16 v[60:63], v[158:161], v[194:197], v[60:63]
	v_mfma_f32_16x16x32_bf16 v[56:59], v[166:169], v[194:197], v[56:59]
	v_mfma_f32_16x16x32_bf16 v[52:55], v[158:161], v[202:205], v[52:55]
	v_mfma_f32_16x16x32_bf16 v[48:51], v[166:169], v[202:205], v[48:51]
	v_mfma_f32_16x16x32_bf16 v[44:47], v[158:161], v[210:213], v[44:47]
	v_mfma_f32_16x16x32_bf16 v[36:39], v[166:169], v[210:213], v[36:39]
	v_mfma_f32_16x16x32_bf16 v[28:31], v[158:161], v[218:221], v[28:31]
	v_mfma_f32_16x16x32_bf16 v[20:23], v[166:169], v[218:221], v[20:23]
	v_mfma_f32_16x16x32_bf16 v[60:63], v[162:165], v[198:201], v[60:63]
	v_mfma_f32_16x16x32_bf16 v[56:59], v[170:173], v[198:201], v[56:59]
	v_mfma_f32_16x16x32_bf16 v[52:55], v[162:165], v[206:209], v[52:55]
	v_mfma_f32_16x16x32_bf16 v[48:51], v[170:173], v[206:209], v[48:51]
	v_mfma_f32_16x16x32_bf16 v[44:47], v[162:165], v[214:217], v[44:47]
	v_mfma_f32_16x16x32_bf16 v[36:39], v[170:173], v[214:217], v[36:39]
	v_mfma_f32_16x16x32_bf16 v[28:31], v[162:165], v[222:225], v[28:31]
	v_mfma_f32_16x16x32_bf16 v[20:23], v[170:173], v[222:225], v[20:23]
	v_mfma_f32_16x16x32_bf16 v[40:43], v[174:177], v[194:197], v[40:43]
	v_mfma_f32_16x16x32_bf16 v[32:35], v[186:189], v[194:197], v[32:35]
	v_mfma_f32_16x16x32_bf16 v[24:27], v[174:177], v[202:205], v[24:27]
	v_mfma_f32_16x16x32_bf16 v[16:19], v[186:189], v[202:205], v[16:19]
	v_mfma_f32_16x16x32_bf16 v[12:15], v[174:177], v[210:213], v[12:15]
	v_mfma_f32_16x16x32_bf16 v[8:11], v[186:189], v[210:213], v[8:11]
	v_mfma_f32_16x16x32_bf16 v[4:7], v[174:177], v[218:221], v[4:7]
	v_mfma_f32_16x16x32_bf16 v[0:3], v[186:189], v[218:221], v[0:3]
	v_mfma_f32_16x16x32_bf16 v[40:43], v[178:181], v[198:201], v[40:43]
	v_mfma_f32_16x16x32_bf16 v[32:35], v[190:193], v[198:201], v[32:35]
	v_mfma_f32_16x16x32_bf16 v[24:27], v[178:181], v[206:209], v[24:27]
	v_mfma_f32_16x16x32_bf16 v[16:19], v[190:193], v[206:209], v[16:19]
	v_mfma_f32_16x16x32_bf16 v[12:15], v[178:181], v[214:217], v[12:15]
	v_mfma_f32_16x16x32_bf16 v[8:11], v[190:193], v[214:217], v[8:11]
	v_mfma_f32_16x16x32_bf16 v[4:7], v[178:181], v[222:225], v[4:7]
	v_mfma_f32_16x16x32_bf16 v[0:3], v[190:193], v[222:225], v[0:3]
	s_barrier
	s_setprio 0
	s_add_i32 s44, s44, 2
	s_add_u32 s0, s0, 0x100
	s_addc_u32 s1, s1, 0
	s_add_u32 s42, s42, 0x100
	s_addc_u32 s43, s43, 0
	s_cmp_gt_u32 s44, 5
	s_cbranch_scc0 .LBB0_470
	s_ashr_i32 s0, s24, 10
	s_ashr_i32 s1, s0, 31
	s_lshl_b64 s[0:1], s[0:1], 23
	v_lshl_add_u64 v[158:159], v[138:139], 0, s[0:1]
	s_lshl_b32 s0, s23, 8
	v_add_u32_e32 v136, s0, v148
	v_lshlrev_b64 v[160:161], 10, v[136:137]
	v_lshl_add_u64 v[160:161], v[158:159], 0, v[160:161]
	global_store_dwordx4 v[160:161], v[124:127], off
	global_store_dwordx4 v[160:161], v[120:123], off offset:16
	global_store_dwordx4 v[160:161], v[104:107], off offset:512
	global_store_dwordx4 v[160:161], v[96:99], off offset:528
	s_and_b64 vcc, exec, vcc
	s_mov_b32 s24, s35
	v_add_u32_e32 v96, s0, v152
	v_mov_b32_e32 v97, v137
	v_lshlrev_b64 v[96:97], 10, v[96:97]
	v_lshl_add_u64 v[96:97], v[158:159], 0, v[96:97]
	global_store_dwordx4 v[96:97], v[116:119], off
	global_store_dwordx4 v[96:97], v[112:115], off offset:16
	global_store_dwordx4 v[96:97], v[88:91], off offset:512
	global_store_dwordx4 v[96:97], v[80:83], off offset:528
	s_mov_b32 s23, s37
	s_nop 0
	v_add_u32_e32 v80, s0, v153
	v_mov_b32_e32 v81, v137
	v_lshlrev_b64 v[80:81], 10, v[80:81]
	v_lshl_add_u64 v[80:81], v[158:159], 0, v[80:81]
	global_store_dwordx4 v[80:81], v[108:111], off
	global_store_dwordx4 v[80:81], v[100:103], off offset:16
	global_store_dwordx4 v[80:81], v[76:79], off offset:512
	global_store_dwordx4 v[80:81], v[72:75], off offset:528
	s_nop 1
	v_add_u32_e32 v72, s0, v154
	v_mov_b32_e32 v73, v137
	v_lshlrev_b64 v[72:73], 10, v[72:73]
	v_lshl_add_u64 v[72:73], v[158:159], 0, v[72:73]
	global_store_dwordx4 v[72:73], v[92:95], off
	global_store_dwordx4 v[72:73], v[84:87], off offset:16
	global_store_dwordx4 v[72:73], v[68:71], off offset:512
	global_store_dwordx4 v[72:73], v[64:67], off offset:528
	s_nop 1
	v_add_u32_e32 v64, 0x80, v136
	v_mov_b32_e32 v65, v137
	v_lshlrev_b64 v[64:65], 10, v[64:65]
	v_lshl_add_u64 v[64:65], v[158:159], 0, v[64:65]
	global_store_dwordx4 v[64:65], v[60:63], off
	global_store_dwordx4 v[64:65], v[56:59], off offset:16
	global_store_dwordx4 v[64:65], v[40:43], off offset:512
	global_store_dwordx4 v[64:65], v[32:35], off offset:528
	s_nop 1
	v_add_u32_e32 v32, 0x90, v136
	v_mov_b32_e32 v33, v137
	v_lshlrev_b64 v[32:33], 10, v[32:33]
	v_lshl_add_u64 v[32:33], v[158:159], 0, v[32:33]
	global_store_dwordx4 v[32:33], v[52:55], off
	global_store_dwordx4 v[32:33], v[48:51], off offset:16
	global_store_dwordx4 v[32:33], v[24:27], off offset:512
	global_store_dwordx4 v[32:33], v[16:19], off offset:528
	s_nop 1
	v_add_u32_e32 v16, 0xa0, v136
	v_mov_b32_e32 v17, v137
	v_lshlrev_b64 v[16:17], 10, v[16:17]
	v_lshl_add_u64 v[16:17], v[158:159], 0, v[16:17]
	v_add_u32_e32 v136, 0xb0, v136
	global_store_dwordx4 v[16:17], v[44:47], off
	global_store_dwordx4 v[16:17], v[36:39], off offset:16
	global_store_dwordx4 v[16:17], v[12:15], off offset:512
	global_store_dwordx4 v[16:17], v[8:11], off offset:528
	s_nop 1
	v_lshlrev_b64 v[8:9], 10, v[136:137]
	v_lshl_add_u64 v[8:9], v[158:159], 0, v[8:9]
	global_store_dwordx4 v[8:9], v[28:31], off
	global_store_dwordx4 v[8:9], v[20:23], off offset:16
	global_store_dwordx4 v[8:9], v[4:7], off offset:512
	global_store_dwordx4 v[8:9], v[0:3], off offset:528
	s_cbranch_vccz .LBB0_469
	s_waitcnt vmcnt(0)
	s_cmpk_gt_u32 s14, 0xff
	s_cbranch_scc1 .LBB0_474
	s_barrier

; #define PG8_STAGE(bufoff, gbase, voff) do { _Pragma("unroll") for (int _i = 0; _i < 2; ++_i) \
;         __builtin_amdgcn_global_load_lds((const unsigned*)((const char*)(gbase) + (voff)[_i]), (PG8_LAS unsigned*)(lds + (bufoff) + ldsw + _i * 8192), 16, 0, 0); } while (0)
; #define PG8_LDA(dst, b, h) do { _Pragma("unroll") for (int m = 0; m < 4; ++m) _Pragma("unroll") for (int k = 0; k < 2; ++k) dst[m][k] = *(const PG8_LAS bf16x8*)(lds + PG8_SA(b, h) + aoff + m * 2048 + k * 1024); } while (0)
; #define PG8_LDB(dst, b, h) do { _Pragma("unroll") for (int n = 0; n < 2; ++n) _Pragma("unroll") for (int k = 0; k < 2; ++k) dst[n][k] = *(const PG8_LAS bf16x8*)(lds + PG8_SB(b, h) + boff + n * 2048 + k * 1024); } while (0)
; #define PG8_MMA(ai, bj, At, Bt) do { __builtin_amdgcn_s_setprio(1); _Pragma("unroll") for (int m = 0; m < 4; ++m) _Pragma("unroll") for (int n = 0; n < 2; ++n) _Pragma("unroll") for (int k = 0; k < 2; ++k) \
;         acc[ai][bj][m][n] = __builtin_amdgcn_mfma_f32_16x16x32_bf16(Bt[n][k], At[m][k], acc[ai][bj][m][n], 0, 0, 0); __builtin_amdgcn_s_setprio(0); } while (0)
; #define PG8_WAIT_V(n) asm volatile("s_waitcnt vmcnt(" #n ")" ::: "memory")
; #define PG8_WAIT_L(n) asm volatile("s_waitcnt lgkmcnt(" #n ")" ::: "memory")
; #define PG8_BAR __builtin_amdgcn_s_barrier()
; #define PG8_SCHED __builtin_amdgcn_sched_barrier(0)
; template <class Epi, class Sched, bool ALIGN_EPI = false, bool SP2 = false>
; __device__ __forceinline__ void gemm_phase(PG8_LAS unsigned char* lds, const Gemm g, const Sched& S, const Epi& E) {
;     ...
;             PG8_LDB(B0, 0, 0); PG8_LDB(B1, 0, 1); PG8_SCHED; PG8_LDA(At, 0, 0); PG8_STAGE(PG8_SA(1, 1), a1 + hstepA, voffA);
;             PG8_WAIT_V(8); PG8_WAIT_L(0); PG8_BAR; PG8_MMA(0, 0, At, B0); PG8_MMA(0, 1, At, B1); PG8_BAR; PG8_SCHED;
;             PG8_LDA(At, 0, 1); PG8_STAGE(PG8_SB(0, 0), b2, voffB); PG8_STAGE(PG8_SB(0, 1), b2 + hstepB, voffB); PG8_STAGE(PG8_SA(0, 0), a2, voffA);
.LBB0_935:
	ds_read_b128 v[120:123], v237
	ds_read_b128 v[124:127], v237 offset:1024
	ds_read_b128 v[136:139], v237 offset:2048
	ds_read_b128 v[140:143], v237 offset:3072
	ds_read_b128 v[144:147], v238
	ds_read_b128 v[148:151], v238 offset:1024
	ds_read_b128 v[152:155], v238 offset:2048
	ds_read_b128 v[156:159], v238 offset:3072
	s_add_u32 s38, s36, 0xfffc0080
	s_addc_u32 s39, s37, -1
	s_cmp_eq_u32 s58, 12
	s_cselect_b32 s41, s9, s39
	s_cselect_b32 s40, s27, s38
	s_cselect_b32 s39, s25, s57
	s_cselect_b32 s38, s35, s56
	v_lshl_add_u64 v[214:215], s[36:37], 0, v[198:199]
	s_add_i32 m0, s44, 0xc000
	ds_read_b128 v[160:163], v239
	ds_read_b128 v[164:167], v239 offset:1024
	ds_read_b128 v[168:171], v239 offset:2048
	ds_read_b128 v[172:175], v239 offset:3072
	ds_read_b128 v[176:179], v239 offset:4096
	ds_read_b128 v[180:183], v239 offset:5120
	ds_read_b128 v[206:209], v239 offset:6144
	ds_read_b128 v[210:213], v239 offset:7168
	global_load_lds_dwordx4 v[214:215], off
	v_lshl_add_u64 v[214:215], s[36:37], 0, v[200:201]
	s_add_i32 m0, s44, 0xe000
	s_nop 0
	global_load_lds_dwordx4 v[214:215], off
	s_waitcnt vmcnt(8) lgkmcnt(0)
	s_setprio 1
	s_barrier
	v_mfma_f32_16x16x32_bf16 v[132:135], v[120:123], v[160:163], v[132:135]
	v_mfma_f32_16x16x32_bf16 v[128:131], v[136:139], v[160:163], v[128:131]
	v_mfma_f32_16x16x32_bf16 v[108:111], v[120:123], v[168:171], v[108:111]
	v_mfma_f32_16x16x32_bf16 v[104:107], v[136:139], v[168:171], v[104:107]
	v_mfma_f32_16x16x32_bf16 v[92:95], v[120:123], v[176:179], v[92:95]
	v_mfma_f32_16x16x32_bf16 v[88:91], v[136:139], v[176:179], v[88:91]
	v_mfma_f32_16x16x32_bf16 v[76:79], v[120:123], v[206:209], v[76:79]
	v_mfma_f32_16x16x32_bf16 v[72:75], v[136:139], v[206:209], v[72:75]
	v_mfma_f32_16x16x32_bf16 v[132:135], v[124:127], v[164:167], v[132:135]
	v_mfma_f32_16x16x32_bf16 v[128:131], v[140:143], v[164:167], v[128:131]
	v_mfma_f32_16x16x32_bf16 v[108:111], v[124:127], v[172:175], v[108:111]
	v_mfma_f32_16x16x32_bf16 v[104:107], v[140:143], v[172:175], v[104:107]
	v_mfma_f32_16x16x32_bf16 v[92:95], v[124:127], v[180:183], v[92:95]
	v_mfma_f32_16x16x32_bf16 v[88:91], v[140:143], v[180:183], v[88:91]
	v_mfma_f32_16x16x32_bf16 v[76:79], v[124:127], v[210:213], v[76:79]
	v_mfma_f32_16x16x32_bf16 v[72:75], v[140:143], v[210:213], v[72:75]
	v_mfma_f32_16x16x32_bf16 v[116:119], v[144:147], v[160:163], v[116:119]
	v_mfma_f32_16x16x32_bf16 v[112:115], v[152:155], v[160:163], v[112:115]
	v_mfma_f32_16x16x32_bf16 v[100:103], v[144:147], v[168:171], v[100:103]
	v_mfma_f32_16x16x32_bf16 v[96:99], v[152:155], v[168:171], v[96:99]
	v_mfma_f32_16x16x32_bf16 v[84:87], v[144:147], v[176:179], v[84:87]
	v_mfma_f32_16x16x32_bf16 v[80:83], v[152:155], v[176:179], v[80:83]
	v_mfma_f32_16x16x32_bf16 v[68:71], v[144:147], v[206:209], v[68:71]
	v_mfma_f32_16x16x32_bf16 v[64:67], v[152:155], v[206:209], v[64:67]
	v_mfma_f32_16x16x32_bf16 v[116:119], v[148:151], v[164:167], v[116:119]
	v_mfma_f32_16x16x32_bf16 v[112:115], v[156:159], v[164:167], v[112:115]
	v_mfma_f32_16x16x32_bf16 v[100:103], v[148:151], v[172:175], v[100:103]
	v_mfma_f32_16x16x32_bf16 v[96:99], v[156:159], v[172:175], v[96:99]
	v_mfma_f32_16x16x32_bf16 v[84:87], v[148:151], v[180:183], v[84:87]
	v_mfma_f32_16x16x32_bf16 v[80:83], v[156:159], v[180:183], v[80:83]
	v_mfma_f32_16x16x32_bf16 v[68:71], v[148:151], v[210:213], v[68:71]
	v_mfma_f32_16x16x32_bf16 v[64:67], v[156:159], v[210:213], v[64:67]
	s_barrier
	s_setprio 0
	s_add_i32 s59, s53, s43
	v_lshl_add_u64 v[214:215], s[38:39], 0, v[188:189]
	s_mov_b32 m0, s59
	ds_read_b128 v[160:163], v239 offset:16384
	ds_read_b128 v[164:167], v239 offset:17408
	ds_read_b128 v[168:171], v239 offset:18432
	ds_read_b128 v[172:175], v239 offset:19456
	ds_read_b128 v[176:179], v239 offset:20480
	ds_read_b128 v[180:183], v239 offset:21504
	ds_read_b128 v[206:209], v239 offset:22528
	ds_read_b128 v[210:213], v239 offset:23552
	global_load_lds_dwordx4 v[214:215], off
	s_add_i32 m0, s59, 0x2000
	s_add_u32 s60, s38, 0x40000
	v_lshl_add_u64 v[216:217], s[38:39], 0, v[192:193]
	s_addc_u32 s61, s39, 0
	s_add_i32 s59, s54, s43
	global_load_lds_dwordx4 v[216:217], off
	v_lshl_add_u64 v[218:219], s[60:61], 0, v[188:189]
	s_mov_b32 m0, s59
	v_lshl_add_u64 v[220:221], s[40:41], 0, v[190:191]
	global_load_lds_dwordx4 v[218:219], off
	v_lshl_add_u64 v[218:219], s[60:61], 0, v[192:193]
	s_add_i32 m0, s59, 0x2000
	s_nop 0
	global_load_lds_dwordx4 v[218:219], off
	v_lshl_add_u64 v[218:219], s[40:41], 0, v[186:187]
	s_mov_b32 m0, s44
	s_nop 0
	global_load_lds_dwordx4 v[218:219], off
	s_mov_b32 m0, s45
	s_nop 0
	global_load_lds_dwordx4 v[220:221], off
	s_waitcnt vmcnt(8) lgkmcnt(0)
	s_setprio 1
	s_barrier
; #define PG8_STAGE(bufoff, gbase, voff) do { _Pragma("unroll") for (int _i = 0; _i < 2; ++_i) \
;         __builtin_amdgcn_global_load_lds((const unsigned*)((const char*)(gbase) + (voff)[_i]), (PG8_LAS unsigned*)(lds + (bufoff) + ldsw + _i * 8192), 16, 0, 0); } while (0)
; #define PG8_LDA(dst, b, h) do { _Pragma("unroll") for (int m = 0; m < 4; ++m) _Pragma("unroll") for (int k = 0; k < 2; ++k) dst[m][k] = *(const PG8_LAS bf16x8*)(lds + PG8_SA(b, h) + aoff + m * 2048 + k * 1024); } while (0)
; #define PG8_LDB(dst, b, h) do { _Pragma("unroll") for (int n = 0; n < 2; ++n) _Pragma("unroll") for (int k = 0; k < 2; ++k) dst[n][k] = *(const PG8_LAS bf16x8*)(lds + PG8_SB(b, h) + boff + n * 2048 + k * 1024); } while (0)
; #define PG8_MMA(ai, bj, At, Bt) do { __builtin_amdgcn_s_setprio(1); _Pragma("unroll") for (int m = 0; m < 4; ++m) _Pragma("unroll") for (int n = 0; n < 2; ++n) _Pragma("unroll") for (int k = 0; k < 2; ++k) \
;         acc[ai][bj][m][n] = __builtin_amdgcn_mfma_f32_16x16x32_bf16(Bt[n][k], At[m][k], acc[ai][bj][m][n], 0, 0, 0); __builtin_amdgcn_s_setprio(0); } while (0)
; #define PG8_WAIT_V(n) asm volatile("s_waitcnt vmcnt(" #n ")" ::: "memory")
; #define PG8_WAIT_L(n) asm volatile("s_waitcnt lgkmcnt(" #n ")" ::: "memory")
; #define PG8_BAR __builtin_amdgcn_s_barrier()
; #define PG8_SCHED __builtin_amdgcn_sched_barrier(0)
; template <class Epi, class Sched, bool ALIGN_EPI = false, bool SP2 = false>
; __device__ __forceinline__ void gemm_phase(PG8_LAS unsigned char* lds, const Gemm g, const Sched& S, const Epi& E) {
;     ...
;             PG8_WAIT_V(8); PG8_WAIT_L(0); PG8_BAR; PG8_MMA(1, 0, At, B0); PG8_MMA(1, 1, At, B1); PG8_BAR; PG8_SCHED;
;             PG8_LDB(B0, 1, 0); PG8_LDB(B1, 1, 1); PG8_SCHED; PG8_LDA(At, 1, 0); PG8_STAGE(PG8_SA(0, 1), a2 + hstepA, voffA);
;             PG8_WAIT_V(8); PG8_WAIT_L(0); PG8_BAR; PG8_MMA(0, 0, At, B0); PG8_MMA(0, 1, At, B1); PG8_BAR; PG8_SCHED;
	v_mfma_f32_16x16x32_bf16 v[60:63], v[120:123], v[160:163], v[60:63]
	v_mfma_f32_16x16x32_bf16 v[56:59], v[136:139], v[160:163], v[56:59]
	v_mfma_f32_16x16x32_bf16 v[44:47], v[120:123], v[168:171], v[44:47]
	v_mfma_f32_16x16x32_bf16 v[40:43], v[136:139], v[168:171], v[40:43]
	v_mfma_f32_16x16x32_bf16 v[28:31], v[120:123], v[176:179], v[28:31]
	v_mfma_f32_16x16x32_bf16 v[24:27], v[136:139], v[176:179], v[24:27]
	v_mfma_f32_16x16x32_bf16 v[12:15], v[120:123], v[206:209], v[12:15]
	v_mfma_f32_16x16x32_bf16 v[8:11], v[136:139], v[206:209], v[8:11]
	v_mfma_f32_16x16x32_bf16 v[60:63], v[124:127], v[164:167], v[60:63]
	v_mfma_f32_16x16x32_bf16 v[56:59], v[140:143], v[164:167], v[56:59]
	v_mfma_f32_16x16x32_bf16 v[44:47], v[124:127], v[172:175], v[44:47]
	v_mfma_f32_16x16x32_bf16 v[40:43], v[140:143], v[172:175], v[40:43]
	v_mfma_f32_16x16x32_bf16 v[28:31], v[124:127], v[180:183], v[28:31]
	v_mfma_f32_16x16x32_bf16 v[24:27], v[140:143], v[180:183], v[24:27]
	v_mfma_f32_16x16x32_bf16 v[12:15], v[124:127], v[210:213], v[12:15]
	v_mfma_f32_16x16x32_bf16 v[8:11], v[140:143], v[210:213], v[8:11]
	v_mfma_f32_16x16x32_bf16 v[52:55], v[144:147], v[160:163], v[52:55]
	v_mfma_f32_16x16x32_bf16 v[48:51], v[152:155], v[160:163], v[48:51]
	v_mfma_f32_16x16x32_bf16 v[36:39], v[144:147], v[168:171], v[36:39]
	v_mfma_f32_16x16x32_bf16 v[32:35], v[152:155], v[168:171], v[32:35]
	v_mfma_f32_16x16x32_bf16 v[20:23], v[144:147], v[176:179], v[20:23]
	v_mfma_f32_16x16x32_bf16 v[16:19], v[152:155], v[176:179], v[16:19]
	v_mfma_f32_16x16x32_bf16 v[4:7], v[144:147], v[206:209], v[4:7]
	v_mfma_f32_16x16x32_bf16 v[0:3], v[152:155], v[206:209], v[0:3]
	v_mfma_f32_16x16x32_bf16 v[52:55], v[148:151], v[164:167], v[52:55]
	v_mfma_f32_16x16x32_bf16 v[48:51], v[156:159], v[164:167], v[48:51]
	v_mfma_f32_16x16x32_bf16 v[36:39], v[148:151], v[172:175], v[36:39]
	v_mfma_f32_16x16x32_bf16 v[32:35], v[156:159], v[172:175], v[32:35]
	v_mfma_f32_16x16x32_bf16 v[20:23], v[148:151], v[180:183], v[20:23]
	v_mfma_f32_16x16x32_bf16 v[16:19], v[156:159], v[180:183], v[16:19]
	v_mfma_f32_16x16x32_bf16 v[4:7], v[148:151], v[210:213], v[4:7]
	v_mfma_f32_16x16x32_bf16 v[0:3], v[156:159], v[210:213], v[0:3]
	s_barrier
	s_setprio 0
	s_add_i32 s59, 0, 0x18000
	s_add_i32 s60, 0, 0x1c000
	v_add_u32_e32 v140, s59, v234
	v_add_u32_e32 v156, s60, v234
	ds_read_b128 v[120:123], v140
	ds_read_b128 v[124:127], v140 offset:1024
	ds_read_b128 v[136:139], v140 offset:2048
	ds_read_b128 v[140:143], v140 offset:3072
	ds_read_b128 v[144:147], v156
	ds_read_b128 v[148:151], v156 offset:1024
	ds_read_b128 v[152:155], v156 offset:2048
	ds_read_b128 v[156:159], v156 offset:3072
	s_add_u32 s40, s40, 0x40000
	s_addc_u32 s41, s41, 0
	s_mov_b32 m0, s46
	v_lshl_add_u64 v[222:223], s[40:41], 0, v[186:187]
	ds_read_b128 v[160:163], v239 offset:32768
	ds_read_b128 v[164:167], v239 offset:33792
	ds_read_b128 v[168:171], v239 offset:34816
	ds_read_b128 v[172:175], v239 offset:35840
	ds_read_b128 v[176:179], v239 offset:36864
	ds_read_b128 v[180:183], v239 offset:37888
	ds_read_b128 v[206:209], v239 offset:38912
	ds_read_b128 v[210:213], v239 offset:39936
	global_load_lds_dwordx4 v[222:223], off
	v_lshl_add_u64 v[222:223], s[40:41], 0, v[190:191]
	s_mov_b32 m0, s47
	s_nop 0
	global_load_lds_dwordx4 v[222:223], off
	s_waitcnt vmcnt(8) lgkmcnt(0)
	s_setprio 1
	s_barrier
	v_mfma_f32_16x16x32_bf16 v[132:135], v[120:123], v[160:163], v[132:135]
	v_mfma_f32_16x16x32_bf16 v[128:131], v[136:139], v[160:163], v[128:131]
	v_mfma_f32_16x16x32_bf16 v[108:111], v[120:123], v[168:171], v[108:111]
	v_mfma_f32_16x16x32_bf16 v[104:107], v[136:139], v[168:171], v[104:107]
	v_mfma_f32_16x16x32_bf16 v[92:95], v[120:123], v[176:179], v[92:95]
	v_mfma_f32_16x16x32_bf16 v[88:91], v[136:139], v[176:179], v[88:91]
	v_mfma_f32_16x16x32_bf16 v[76:79], v[120:123], v[206:209], v[76:79]
	v_mfma_f32_16x16x32_bf16 v[72:75], v[136:139], v[206:209], v[72:75]
	v_mfma_f32_16x16x32_bf16 v[132:135], v[124:127], v[164:167], v[132:135]
	v_mfma_f32_16x16x32_bf16 v[128:131], v[140:143], v[164:167], v[128:131]
	v_mfma_f32_16x16x32_bf16 v[108:111], v[124:127], v[172:175], v[108:111]
	v_mfma_f32_16x16x32_bf16 v[104:107], v[140:143], v[172:175], v[104:107]
	v_mfma_f32_16x16x32_bf16 v[92:95], v[124:127], v[180:183], v[92:95]
	v_mfma_f32_16x16x32_bf16 v[88:91], v[140:143], v[180:183], v[88:91]
	v_mfma_f32_16x16x32_bf16 v[76:79], v[124:127], v[210:213], v[76:79]
	v_mfma_f32_16x16x32_bf16 v[72:75], v[140:143], v[210:213], v[72:75]
	v_mfma_f32_16x16x32_bf16 v[116:119], v[144:147], v[160:163], v[116:119]
	v_mfma_f32_16x16x32_bf16 v[112:115], v[152:155], v[160:163], v[112:115]
	v_mfma_f32_16x16x32_bf16 v[100:103], v[144:147], v[168:171], v[100:103]
	v_mfma_f32_16x16x32_bf16 v[96:99], v[152:155], v[168:171], v[96:99]
	v_mfma_f32_16x16x32_bf16 v[84:87], v[144:147], v[176:179], v[84:87]
	v_mfma_f32_16x16x32_bf16 v[80:83], v[152:155], v[176:179], v[80:83]
	v_mfma_f32_16x16x32_bf16 v[68:71], v[144:147], v[206:209], v[68:71]
	v_mfma_f32_16x16x32_bf16 v[64:67], v[152:155], v[206:209], v[64:67]
	v_mfma_f32_16x16x32_bf16 v[116:119], v[148:151], v[164:167], v[116:119]
	v_mfma_f32_16x16x32_bf16 v[112:115], v[156:159], v[164:167], v[112:115]
	v_mfma_f32_16x16x32_bf16 v[100:103], v[148:151], v[172:175], v[100:103]
	v_mfma_f32_16x16x32_bf16 v[96:99], v[156:159], v[172:175], v[96:99]
	v_mfma_f32_16x16x32_bf16 v[84:87], v[148:151], v[180:183], v[84:87]
	v_mfma_f32_16x16x32_bf16 v[80:83], v[156:159], v[180:183], v[80:83]
	v_mfma_f32_16x16x32_bf16 v[68:71], v[148:151], v[210:213], v[68:71]
	v_mfma_f32_16x16x32_bf16 v[64:67], v[156:159], v[210:213], v[64:67]
	s_barrier
; #define PG8_STAGE(bufoff, gbase, voff) do { _Pragma("unroll") for (int _i = 0; _i < 2; ++_i) \
;         __builtin_amdgcn_global_load_lds((const unsigned*)((const char*)(gbase) + (voff)[_i]), (PG8_LAS unsigned*)(lds + (bufoff) + ldsw + _i * 8192), 16, 0, 0); } while (0)
; #define PG8_LDA(dst, b, h) do { _Pragma("unroll") for (int m = 0; m < 4; ++m) _Pragma("unroll") for (int k = 0; k < 2; ++k) dst[m][k] = *(const PG8_LAS bf16x8*)(lds + PG8_SA(b, h) + aoff + m * 2048 + k * 1024); } while (0)
; #define PG8_MMA(ai, bj, At, Bt) do { __builtin_amdgcn_s_setprio(1); _Pragma("unroll") for (int m = 0; m < 4; ++m) _Pragma("unroll") for (int n = 0; n < 2; ++n) _Pragma("unroll") for (int k = 0; k < 2; ++k) \
;         acc[ai][bj][m][n] = __builtin_amdgcn_mfma_f32_16x16x32_bf16(Bt[n][k], At[m][k], acc[ai][bj][m][n], 0, 0, 0); __builtin_amdgcn_s_setprio(0); } while (0)
; #define PG8_WAIT_V(n) asm volatile("s_waitcnt vmcnt(" #n ")" ::: "memory")
; #define PG8_WAIT_L(n) asm volatile("s_waitcnt lgkmcnt(" #n ")" ::: "memory")
; #define PG8_BAR __builtin_amdgcn_s_barrier()
; #define PG8_SCHED __builtin_amdgcn_sched_barrier(0)
; template <class Epi, class Sched, bool ALIGN_EPI = false, bool SP2 = false>
; __device__ __forceinline__ void gemm_phase(PG8_LAS unsigned char* lds, const Gemm g, const Sched& S, const Epi& E) {
;     ...
;             PG8_LDA(At, 1, 1); PG8_STAGE(PG8_SB(1, 0), b3, voffB); PG8_STAGE(PG8_SB(1, 1), b3 + hstepB, voffB); PG8_STAGE(PG8_SA(1, 0), a3, voffA);
;             PG8_WAIT_V(8); PG8_WAIT_L(0); PG8_BAR; PG8_MMA(1, 0, At, B0); PG8_MMA(1, 1, At, B1); PG8_BAR; PG8_SCHED;
;     ...
;         if constexpr (ALIGN_EPI) { if (wr == 0) PG8_BAR; }
	s_setprio 0
	s_add_i32 s40, s59, s43
	v_lshl_add_u64 v[214:215], v[214:215], 0, s[20:21]
	s_mov_b32 m0, s40
	ds_read_b128 v[160:163], v239 offset:49152
	ds_read_b128 v[164:167], v239 offset:50176
	ds_read_b128 v[168:171], v239 offset:51200
	ds_read_b128 v[172:175], v239 offset:52224
	ds_read_b128 v[176:179], v239 offset:53248
	ds_read_b128 v[180:183], v239 offset:54272
	ds_read_b128 v[206:209], v239 offset:55296
	ds_read_b128 v[210:213], v239 offset:56320
	global_load_lds_dwordx4 v[214:215], off
	s_add_i32 m0, s40, 0x2000
	s_add_u32 s38, s38, 0x40080
	v_lshl_add_u64 v[214:215], v[216:217], 0, s[20:21]
	s_addc_u32 s39, s39, 0
	s_add_i32 s40, s60, s43
	global_load_lds_dwordx4 v[214:215], off
	v_lshl_add_u64 v[214:215], s[38:39], 0, v[188:189]
	s_mov_b32 m0, s40
	s_nop 0
	global_load_lds_dwordx4 v[214:215], off
	v_lshl_add_u64 v[214:215], s[38:39], 0, v[192:193]
	s_add_i32 m0, s40, 0x2000
	s_nop 0
	global_load_lds_dwordx4 v[214:215], off
	v_lshl_add_u64 v[214:215], v[218:219], 0, s[20:21]
	s_mov_b32 m0, s48
	s_nop 0
	global_load_lds_dwordx4 v[214:215], off
	v_lshl_add_u64 v[214:215], v[220:221], 0, s[20:21]
	s_mov_b32 m0, s49
	s_nop 0
	global_load_lds_dwordx4 v[214:215], off
	s_waitcnt vmcnt(8) lgkmcnt(0)
	s_setprio 1
	s_barrier
	v_mfma_f32_16x16x32_bf16 v[60:63], v[120:123], v[160:163], v[60:63]
	v_mfma_f32_16x16x32_bf16 v[56:59], v[136:139], v[160:163], v[56:59]
	v_mfma_f32_16x16x32_bf16 v[44:47], v[120:123], v[168:171], v[44:47]
	v_mfma_f32_16x16x32_bf16 v[40:43], v[136:139], v[168:171], v[40:43]
	v_mfma_f32_16x16x32_bf16 v[28:31], v[120:123], v[176:179], v[28:31]
	v_mfma_f32_16x16x32_bf16 v[24:27], v[136:139], v[176:179], v[24:27]
	v_mfma_f32_16x16x32_bf16 v[12:15], v[120:123], v[206:209], v[12:15]
	v_mfma_f32_16x16x32_bf16 v[8:11], v[136:139], v[206:209], v[8:11]
	v_mfma_f32_16x16x32_bf16 v[60:63], v[124:127], v[164:167], v[60:63]
	v_mfma_f32_16x16x32_bf16 v[56:59], v[140:143], v[164:167], v[56:59]
	v_mfma_f32_16x16x32_bf16 v[44:47], v[124:127], v[172:175], v[44:47]
	v_mfma_f32_16x16x32_bf16 v[40:43], v[140:143], v[172:175], v[40:43]
	v_mfma_f32_16x16x32_bf16 v[28:31], v[124:127], v[180:183], v[28:31]
	v_mfma_f32_16x16x32_bf16 v[24:27], v[140:143], v[180:183], v[24:27]
	v_mfma_f32_16x16x32_bf16 v[12:15], v[124:127], v[210:213], v[12:15]
	v_mfma_f32_16x16x32_bf16 v[8:11], v[140:143], v[210:213], v[8:11]
	v_mfma_f32_16x16x32_bf16 v[52:55], v[144:147], v[160:163], v[52:55]
	v_mfma_f32_16x16x32_bf16 v[48:51], v[152:155], v[160:163], v[48:51]
	v_mfma_f32_16x16x32_bf16 v[36:39], v[144:147], v[168:171], v[36:39]
	v_mfma_f32_16x16x32_bf16 v[32:35], v[152:155], v[168:171], v[32:35]
	v_mfma_f32_16x16x32_bf16 v[20:23], v[144:147], v[176:179], v[20:23]
	v_mfma_f32_16x16x32_bf16 v[16:19], v[152:155], v[176:179], v[16:19]
	v_mfma_f32_16x16x32_bf16 v[4:7], v[144:147], v[206:209], v[4:7]
	v_mfma_f32_16x16x32_bf16 v[0:3], v[152:155], v[206:209], v[0:3]
	v_mfma_f32_16x16x32_bf16 v[52:55], v[148:151], v[164:167], v[52:55]
	v_mfma_f32_16x16x32_bf16 v[48:51], v[156:159], v[164:167], v[48:51]
	v_mfma_f32_16x16x32_bf16 v[36:39], v[148:151], v[172:175], v[36:39]
	v_mfma_f32_16x16x32_bf16 v[32:35], v[156:159], v[172:175], v[32:35]
	v_mfma_f32_16x16x32_bf16 v[20:23], v[148:151], v[180:183], v[20:23]
	v_mfma_f32_16x16x32_bf16 v[16:19], v[156:159], v[180:183], v[16:19]
	v_mfma_f32_16x16x32_bf16 v[4:7], v[148:151], v[210:213], v[4:7]
	v_mfma_f32_16x16x32_bf16 v[0:3], v[156:159], v[210:213], v[0:3]
	s_barrier
	s_setprio 0
	s_add_i32 s58, s58, 2
	s_add_u32 s36, s36, 0x100
	s_addc_u32 s37, s37, 0
	s_add_u32 s56, s56, 0x100
	s_addc_u32 s57, s57, 0
	s_cmp_gt_u32 s58, 13
	s_cbranch_scc0 .LBB0_935
	s_and_b64 vcc, exec, s[22:23]
	s_cbranch_vccz .LBB0_938
	s_barrier

; #define PG8_STAGE(bufoff, gbase, voff) do { _Pragma("unroll") for (int _i = 0; _i < 2; ++_i) \
;         __builtin_amdgcn_global_load_lds((const unsigned*)((const char*)(gbase) + (voff)[_i]), (PG8_LAS unsigned*)(lds + (bufoff) + ldsw + _i * 8192), 16, 0, 0); } while (0)
; #define PG8_LDA(dst, b, h) do { _Pragma("unroll") for (int m = 0; m < 4; ++m) _Pragma("unroll") for (int k = 0; k < 2; ++k) dst[m][k] = *(const PG8_LAS bf16x8*)(lds + PG8_SA(b, h) + aoff + m * 2048 + k * 1024); } while (0)
; #define PG8_LDB(dst, b, h) do { _Pragma("unroll") for (int n = 0; n < 2; ++n) _Pragma("unroll") for (int k = 0; k < 2; ++k) dst[n][k] = *(const PG8_LAS bf16x8*)(lds + PG8_SB(b, h) + boff + n * 2048 + k * 1024); } while (0)
; #define PG8_MMA(ai, bj, At, Bt) do { __builtin_amdgcn_s_setprio(1); _Pragma("unroll") for (int m = 0; m < 4; ++m) _Pragma("unroll") for (int n = 0; n < 2; ++n) _Pragma("unroll") for (int k = 0; k < 2; ++k) \
;         acc[ai][bj][m][n] = __builtin_amdgcn_mfma_f32_16x16x32_bf16(Bt[n][k], At[m][k], acc[ai][bj][m][n], 0, 0, 0); __builtin_amdgcn_s_setprio(0); } while (0)
; #define PG8_WAIT_V(n) asm volatile("s_waitcnt vmcnt(" #n ")" ::: "memory")
; #define PG8_WAIT_L(n) asm volatile("s_waitcnt lgkmcnt(" #n ")" ::: "memory")
; #define PG8_BAR __builtin_amdgcn_s_barrier()
; #define PG8_SCHED __builtin_amdgcn_sched_barrier(0)
; template <class Epi, class Sched, bool ALIGN_EPI = false, bool SP2 = false>
; __device__ __forceinline__ void gemm_phase(PG8_LAS unsigned char* lds, const Gemm g, const Sched& S, const Epi& E) {
;     ...
;             PG8_LDB(B0, 0, 0); PG8_LDB(B1, 0, 1); PG8_SCHED; PG8_LDA(At, 0, 0); PG8_STAGE(PG8_SA(1, 1), a1 + hstepA, voffA);
;             PG8_WAIT_V(8); PG8_WAIT_L(0); PG8_BAR; PG8_MMA(0, 0, At, B0); PG8_MMA(0, 1, At, B1); PG8_BAR; PG8_SCHED;
;             PG8_LDA(At, 0, 1); PG8_STAGE(PG8_SB(0, 0), b2, voffB); PG8_STAGE(PG8_SB(0, 1), b2 + hstepB, voffB); PG8_STAGE(PG8_SA(0, 0), a2, voffA);
;             PG8_WAIT_V(8); PG8_WAIT_L(0); PG8_BAR; PG8_MMA(1, 0, At, B0); PG8_MMA(1, 1, At, B1); PG8_BAR; PG8_SCHED;
.LBB0_1007:
	ds_read_b128 v[128:131], v176
	ds_read_b128 v[132:135], v176 offset:1024
	ds_read_b128 v[136:139], v176 offset:2048
	ds_read_b128 v[140:143], v176 offset:3072
	ds_read_b128 v[162:165], v177
	ds_read_b128 v[166:169], v177 offset:1024
	ds_read_b128 v[170:173], v177 offset:2048
	ds_read_b128 v[180:183], v177 offset:3072
	s_add_u32 s36, s34, 0xfffc0080
	s_addc_u32 s37, s35, -1
	s_cmp_eq_u32 s56, 12
	s_cselect_b32 s39, s25, s37
	s_cselect_b32 s38, s52, s36
	s_cselect_b32 s37, s23, s55
	s_cselect_b32 s36, s53, s54
	s_add_i32 m0, s41, 0xc000
	ds_read_b128 v[186:189], v178
	ds_read_b128 v[190:193], v178 offset:1024
	ds_read_b128 v[194:197], v178 offset:2048
	ds_read_b128 v[198:201], v178 offset:3072
	ds_read_b128 v[202:205], v178 offset:4096
	ds_read_b128 v[206:209], v178 offset:5120
	ds_read_b128 v[210:213], v178 offset:6144
	ds_read_b128 v[214:217], v178 offset:7168
	global_load_lds_dwordx4 v154, s[34:35]
	s_add_i32 m0, s41, 0xe000
	s_nop 0
	global_load_lds_dwordx4 v156, s[34:35]
	s_waitcnt vmcnt(8) lgkmcnt(0)
	s_setprio 1
	s_barrier
	v_mfma_f32_16x16x32_bf16 v[124:127], v[128:131], v[186:189], v[124:127]
	v_mfma_f32_16x16x32_bf16 v[120:123], v[136:139], v[186:189], v[120:123]
	v_mfma_f32_16x16x32_bf16 v[108:111], v[128:131], v[194:197], v[108:111]
	v_mfma_f32_16x16x32_bf16 v[104:107], v[136:139], v[194:197], v[104:107]
	v_mfma_f32_16x16x32_bf16 v[92:95], v[128:131], v[202:205], v[92:95]
	v_mfma_f32_16x16x32_bf16 v[88:91], v[136:139], v[202:205], v[88:91]
	v_mfma_f32_16x16x32_bf16 v[76:79], v[128:131], v[210:213], v[76:79]
	v_mfma_f32_16x16x32_bf16 v[72:75], v[136:139], v[210:213], v[72:75]
	v_mfma_f32_16x16x32_bf16 v[124:127], v[132:135], v[190:193], v[124:127]
	v_mfma_f32_16x16x32_bf16 v[120:123], v[140:143], v[190:193], v[120:123]
	v_mfma_f32_16x16x32_bf16 v[108:111], v[132:135], v[198:201], v[108:111]
	v_mfma_f32_16x16x32_bf16 v[104:107], v[140:143], v[198:201], v[104:107]
	v_mfma_f32_16x16x32_bf16 v[92:95], v[132:135], v[206:209], v[92:95]
	v_mfma_f32_16x16x32_bf16 v[88:91], v[140:143], v[206:209], v[88:91]
	v_mfma_f32_16x16x32_bf16 v[76:79], v[132:135], v[214:217], v[76:79]
	v_mfma_f32_16x16x32_bf16 v[72:75], v[140:143], v[214:217], v[72:75]
	v_mfma_f32_16x16x32_bf16 v[116:119], v[162:165], v[186:189], v[116:119]
	v_mfma_f32_16x16x32_bf16 v[112:115], v[170:173], v[186:189], v[112:115]
	v_mfma_f32_16x16x32_bf16 v[100:103], v[162:165], v[194:197], v[100:103]
	v_mfma_f32_16x16x32_bf16 v[96:99], v[170:173], v[194:197], v[96:99]
	v_mfma_f32_16x16x32_bf16 v[84:87], v[162:165], v[202:205], v[84:87]
	v_mfma_f32_16x16x32_bf16 v[80:83], v[170:173], v[202:205], v[80:83]
	v_mfma_f32_16x16x32_bf16 v[68:71], v[162:165], v[210:213], v[68:71]
	v_mfma_f32_16x16x32_bf16 v[64:67], v[170:173], v[210:213], v[64:67]
	v_mfma_f32_16x16x32_bf16 v[116:119], v[166:169], v[190:193], v[116:119]
	v_mfma_f32_16x16x32_bf16 v[112:115], v[180:183], v[190:193], v[112:115]
	v_mfma_f32_16x16x32_bf16 v[100:103], v[166:169], v[198:201], v[100:103]
	v_mfma_f32_16x16x32_bf16 v[96:99], v[180:183], v[198:201], v[96:99]
	v_mfma_f32_16x16x32_bf16 v[84:87], v[166:169], v[206:209], v[84:87]
	v_mfma_f32_16x16x32_bf16 v[80:83], v[180:183], v[206:209], v[80:83]
	v_mfma_f32_16x16x32_bf16 v[68:71], v[166:169], v[214:217], v[68:71]
	v_mfma_f32_16x16x32_bf16 v[64:67], v[180:183], v[214:217], v[64:67]
	s_barrier
	s_setprio 0
	s_add_i32 s57, s48, s40
	s_mov_b32 m0, s57
	ds_read_b128 v[186:189], v178 offset:16384
	ds_read_b128 v[190:193], v178 offset:17408
	ds_read_b128 v[194:197], v178 offset:18432
	ds_read_b128 v[198:201], v178 offset:19456
	ds_read_b128 v[202:205], v178 offset:20480
	ds_read_b128 v[206:209], v178 offset:21504
	ds_read_b128 v[210:213], v178 offset:22528
	ds_read_b128 v[214:217], v178 offset:23552
	global_load_lds_dwordx4 v146, s[36:37]
	s_add_i32 m0, s57, 0x2000
	s_add_u32 s58, s36, 0x40000
	s_addc_u32 s59, s37, 0
	s_add_u32 s80, s38, s12
	s_addc_u32 s81, s39, s13
	s_add_i32 s57, s49, s40
	global_load_lds_dwordx4 v150, s[36:37]
	s_mov_b32 m0, s57
	s_nop 0
	global_load_lds_dwordx4 v146, s[58:59]
	s_add_i32 m0, s57, 0x2000
	s_nop 0
	global_load_lds_dwordx4 v150, s[58:59]
	s_mov_b32 m0, s41
	s_nop 0
	global_load_lds_dwordx4 v144, s[38:39]
	s_mov_b32 m0, s42
	s_nop 0
	global_load_lds_dwordx4 v148, s[38:39]
	s_waitcnt vmcnt(8) lgkmcnt(0)
	s_setprio 1
	s_barrier
	v_mfma_f32_16x16x32_bf16 v[60:63], v[128:131], v[186:189], v[60:63]
	v_mfma_f32_16x16x32_bf16 v[56:59], v[136:139], v[186:189], v[56:59]
	v_mfma_f32_16x16x32_bf16 v[44:47], v[128:131], v[194:197], v[44:47]
	v_mfma_f32_16x16x32_bf16 v[40:43], v[136:139], v[194:197], v[40:43]
	v_mfma_f32_16x16x32_bf16 v[28:31], v[128:131], v[202:205], v[28:31]
	v_mfma_f32_16x16x32_bf16 v[24:27], v[136:139], v[202:205], v[24:27]
	v_mfma_f32_16x16x32_bf16 v[12:15], v[128:131], v[210:213], v[12:15]
	v_mfma_f32_16x16x32_bf16 v[8:11], v[136:139], v[210:213], v[8:11]
	v_mfma_f32_16x16x32_bf16 v[60:63], v[132:135], v[190:193], v[60:63]
	v_mfma_f32_16x16x32_bf16 v[56:59], v[140:143], v[190:193], v[56:59]
	v_mfma_f32_16x16x32_bf16 v[44:47], v[132:135], v[198:201], v[44:47]
	v_mfma_f32_16x16x32_bf16 v[40:43], v[140:143], v[198:201], v[40:43]
	v_mfma_f32_16x16x32_bf16 v[28:31], v[132:135], v[206:209], v[28:31]
	v_mfma_f32_16x16x32_bf16 v[24:27], v[140:143], v[206:209], v[24:27]
	v_mfma_f32_16x16x32_bf16 v[12:15], v[132:135], v[214:217], v[12:15]
	v_mfma_f32_16x16x32_bf16 v[8:11], v[140:143], v[214:217], v[8:11]
	v_mfma_f32_16x16x32_bf16 v[52:55], v[162:165], v[186:189], v[52:55]
	v_mfma_f32_16x16x32_bf16 v[48:51], v[170:173], v[186:189], v[48:51]
	v_mfma_f32_16x16x32_bf16 v[36:39], v[162:165], v[194:197], v[36:39]
	v_mfma_f32_16x16x32_bf16 v[32:35], v[170:173], v[194:197], v[32:35]
	v_mfma_f32_16x16x32_bf16 v[20:23], v[162:165], v[202:205], v[20:23]
	v_mfma_f32_16x16x32_bf16 v[16:19], v[170:173], v[202:205], v[16:19]
	v_mfma_f32_16x16x32_bf16 v[4:7], v[162:165], v[210:213], v[4:7]
	v_mfma_f32_16x16x32_bf16 v[0:3], v[170:173], v[210:213], v[0:3]
	v_mfma_f32_16x16x32_bf16 v[52:55], v[166:169], v[190:193], v[52:55]
	v_mfma_f32_16x16x32_bf16 v[48:51], v[180:183], v[190:193], v[48:51]
	v_mfma_f32_16x16x32_bf16 v[36:39], v[166:169], v[198:201], v[36:39]
	v_mfma_f32_16x16x32_bf16 v[32:35], v[180:183], v[198:201], v[32:35]
	v_mfma_f32_16x16x32_bf16 v[20:23], v[166:169], v[206:209], v[20:23]
	v_mfma_f32_16x16x32_bf16 v[16:19], v[180:183], v[206:209], v[16:19]
	v_mfma_f32_16x16x32_bf16 v[4:7], v[166:169], v[214:217], v[4:7]
	v_mfma_f32_16x16x32_bf16 v[0:3], v[180:183], v[214:217], v[0:3]
	s_barrier
; #define PG8_STAGE(bufoff, gbase, voff) do { _Pragma("unroll") for (int _i = 0; _i < 2; ++_i) \
;         __builtin_amdgcn_global_load_lds((const unsigned*)((const char*)(gbase) + (voff)[_i]), (PG8_LAS unsigned*)(lds + (bufoff) + ldsw + _i * 8192), 16, 0, 0); } while (0)
; #define PG8_LDA(dst, b, h) do { _Pragma("unroll") for (int m = 0; m < 4; ++m) _Pragma("unroll") for (int k = 0; k < 2; ++k) dst[m][k] = *(const PG8_LAS bf16x8*)(lds + PG8_SA(b, h) + aoff + m * 2048 + k * 1024); } while (0)
; #define PG8_LDB(dst, b, h) do { _Pragma("unroll") for (int n = 0; n < 2; ++n) _Pragma("unroll") for (int k = 0; k < 2; ++k) dst[n][k] = *(const PG8_LAS bf16x8*)(lds + PG8_SB(b, h) + boff + n * 2048 + k * 1024); } while (0)
; #define PG8_MMA(ai, bj, At, Bt) do { __builtin_amdgcn_s_setprio(1); _Pragma("unroll") for (int m = 0; m < 4; ++m) _Pragma("unroll") for (int n = 0; n < 2; ++n) _Pragma("unroll") for (int k = 0; k < 2; ++k) \
;         acc[ai][bj][m][n] = __builtin_amdgcn_mfma_f32_16x16x32_bf16(Bt[n][k], At[m][k], acc[ai][bj][m][n], 0, 0, 0); __builtin_amdgcn_s_setprio(0); } while (0)
; #define PG8_WAIT_V(n) asm volatile("s_waitcnt vmcnt(" #n ")" ::: "memory")
; #define PG8_WAIT_L(n) asm volatile("s_waitcnt lgkmcnt(" #n ")" ::: "memory")
; #define PG8_BAR __builtin_amdgcn_s_barrier()
; #define PG8_SCHED __builtin_amdgcn_sched_barrier(0)
; template <class Epi, class Sched, bool ALIGN_EPI = false, bool SP2 = false>
; __device__ __forceinline__ void gemm_phase(PG8_LAS unsigned char* lds, const Gemm g, const Sched& S, const Epi& E) {
;     ...
;             PG8_LDB(B0, 1, 0); PG8_LDB(B1, 1, 1); PG8_SCHED; PG8_LDA(At, 1, 0); PG8_STAGE(PG8_SA(0, 1), a2 + hstepA, voffA);
;             PG8_WAIT_V(8); PG8_WAIT_L(0); PG8_BAR; PG8_MMA(0, 0, At, B0); PG8_MMA(0, 1, At, B1); PG8_BAR; PG8_SCHED;
;             PG8_LDA(At, 1, 1); PG8_STAGE(PG8_SB(1, 0), b3, voffB); PG8_STAGE(PG8_SB(1, 1), b3 + hstepB, voffB); PG8_STAGE(PG8_SA(1, 0), a3, voffA);
;             PG8_WAIT_V(8); PG8_WAIT_L(0); PG8_BAR; PG8_MMA(1, 0, At, B0); PG8_MMA(1, 1, At, B1); PG8_BAR; PG8_SCHED;
;     ...
;         if constexpr (ALIGN_EPI) { if (wr == 0) PG8_BAR; }
	s_setprio 0
	s_add_i32 s57, 0, 0x18000
	s_add_i32 s58, 0, 0x1c000
	v_add_u32_e32 v140, s57, v175
	v_add_u32_e32 v179, s58, v175
	ds_read_b128 v[128:131], v140
	ds_read_b128 v[132:135], v140 offset:1024
	ds_read_b128 v[136:139], v140 offset:2048
	ds_read_b128 v[140:143], v140 offset:3072
	ds_read_b128 v[162:165], v179
	ds_read_b128 v[166:169], v179 offset:1024
	ds_read_b128 v[170:173], v179 offset:2048
	ds_read_b128 v[180:183], v179 offset:3072
	s_add_u32 s38, s38, 0x40000
	s_addc_u32 s39, s39, 0
	s_mov_b32 m0, s43
	ds_read_b128 v[186:189], v178 offset:32768
	ds_read_b128 v[190:193], v178 offset:33792
	ds_read_b128 v[194:197], v178 offset:34816
	ds_read_b128 v[198:201], v178 offset:35840
	ds_read_b128 v[202:205], v178 offset:36864
	ds_read_b128 v[206:209], v178 offset:37888
	ds_read_b128 v[210:213], v178 offset:38912
	ds_read_b128 v[214:217], v178 offset:39936
	global_load_lds_dwordx4 v144, s[38:39]
	s_mov_b32 m0, s44
	s_nop 0
	global_load_lds_dwordx4 v148, s[38:39]
	s_waitcnt vmcnt(8) lgkmcnt(0)
	s_setprio 1
	s_barrier
	v_mfma_f32_16x16x32_bf16 v[124:127], v[128:131], v[186:189], v[124:127]
	v_mfma_f32_16x16x32_bf16 v[120:123], v[136:139], v[186:189], v[120:123]
	v_mfma_f32_16x16x32_bf16 v[108:111], v[128:131], v[194:197], v[108:111]
	v_mfma_f32_16x16x32_bf16 v[104:107], v[136:139], v[194:197], v[104:107]
	v_mfma_f32_16x16x32_bf16 v[92:95], v[128:131], v[202:205], v[92:95]
	v_mfma_f32_16x16x32_bf16 v[88:91], v[136:139], v[202:205], v[88:91]
	v_mfma_f32_16x16x32_bf16 v[76:79], v[128:131], v[210:213], v[76:79]
	v_mfma_f32_16x16x32_bf16 v[72:75], v[136:139], v[210:213], v[72:75]
	v_mfma_f32_16x16x32_bf16 v[124:127], v[132:135], v[190:193], v[124:127]
	v_mfma_f32_16x16x32_bf16 v[120:123], v[140:143], v[190:193], v[120:123]
	v_mfma_f32_16x16x32_bf16 v[108:111], v[132:135], v[198:201], v[108:111]
	v_mfma_f32_16x16x32_bf16 v[104:107], v[140:143], v[198:201], v[104:107]
	v_mfma_f32_16x16x32_bf16 v[92:95], v[132:135], v[206:209], v[92:95]
	v_mfma_f32_16x16x32_bf16 v[88:91], v[140:143], v[206:209], v[88:91]
	v_mfma_f32_16x16x32_bf16 v[76:79], v[132:135], v[214:217], v[76:79]
	v_mfma_f32_16x16x32_bf16 v[72:75], v[140:143], v[214:217], v[72:75]
	v_mfma_f32_16x16x32_bf16 v[116:119], v[162:165], v[186:189], v[116:119]
	v_mfma_f32_16x16x32_bf16 v[112:115], v[170:173], v[186:189], v[112:115]
	v_mfma_f32_16x16x32_bf16 v[100:103], v[162:165], v[194:197], v[100:103]
	v_mfma_f32_16x16x32_bf16 v[96:99], v[170:173], v[194:197], v[96:99]
	v_mfma_f32_16x16x32_bf16 v[84:87], v[162:165], v[202:205], v[84:87]
	v_mfma_f32_16x16x32_bf16 v[80:83], v[170:173], v[202:205], v[80:83]
	v_mfma_f32_16x16x32_bf16 v[68:71], v[162:165], v[210:213], v[68:71]
	v_mfma_f32_16x16x32_bf16 v[64:67], v[170:173], v[210:213], v[64:67]
	v_mfma_f32_16x16x32_bf16 v[116:119], v[166:169], v[190:193], v[116:119]
	v_mfma_f32_16x16x32_bf16 v[112:115], v[180:183], v[190:193], v[112:115]
	v_mfma_f32_16x16x32_bf16 v[100:103], v[166:169], v[198:201], v[100:103]
	v_mfma_f32_16x16x32_bf16 v[96:99], v[180:183], v[198:201], v[96:99]
	v_mfma_f32_16x16x32_bf16 v[84:87], v[166:169], v[206:209], v[84:87]
	v_mfma_f32_16x16x32_bf16 v[80:83], v[180:183], v[206:209], v[80:83]
	v_mfma_f32_16x16x32_bf16 v[68:71], v[166:169], v[214:217], v[68:71]
	v_mfma_f32_16x16x32_bf16 v[64:67], v[180:183], v[214:217], v[64:67]
	s_barrier
	s_setprio 0
	s_add_i32 s38, s57, s40
	s_add_u32 s82, s36, s12
	s_addc_u32 s83, s37, s13
	s_mov_b32 m0, s38
	ds_read_b128 v[186:189], v178 offset:49152
	ds_read_b128 v[190:193], v178 offset:50176
	ds_read_b128 v[194:197], v178 offset:51200
	ds_read_b128 v[198:201], v178 offset:52224
	ds_read_b128 v[202:205], v178 offset:53248
	ds_read_b128 v[206:209], v178 offset:54272
	ds_read_b128 v[210:213], v178 offset:55296
	ds_read_b128 v[214:217], v178 offset:56320
	global_load_lds_dwordx4 v146, s[82:83]
	s_add_i32 m0, s38, 0x2000
	s_add_u32 s36, s36, 0x40080
	s_addc_u32 s37, s37, 0
	s_add_i32 s38, s58, s40
	global_load_lds_dwordx4 v150, s[82:83]
	s_mov_b32 m0, s38
	s_nop 0
	global_load_lds_dwordx4 v146, s[36:37]
	s_add_i32 m0, s38, 0x2000
	s_nop 0
	global_load_lds_dwordx4 v150, s[36:37]
	s_mov_b32 m0, s45
	s_nop 0
	global_load_lds_dwordx4 v144, s[80:81]
	s_mov_b32 m0, s46
	s_nop 0
	global_load_lds_dwordx4 v148, s[80:81]
	s_waitcnt vmcnt(8) lgkmcnt(0)
	s_setprio 1
	s_barrier
	v_mfma_f32_16x16x32_bf16 v[60:63], v[128:131], v[186:189], v[60:63]
	v_mfma_f32_16x16x32_bf16 v[56:59], v[136:139], v[186:189], v[56:59]
	v_mfma_f32_16x16x32_bf16 v[44:47], v[128:131], v[194:197], v[44:47]
	v_mfma_f32_16x16x32_bf16 v[40:43], v[136:139], v[194:197], v[40:43]
	v_mfma_f32_16x16x32_bf16 v[28:31], v[128:131], v[202:205], v[28:31]
	v_mfma_f32_16x16x32_bf16 v[24:27], v[136:139], v[202:205], v[24:27]
	v_mfma_f32_16x16x32_bf16 v[12:15], v[128:131], v[210:213], v[12:15]
	v_mfma_f32_16x16x32_bf16 v[8:11], v[136:139], v[210:213], v[8:11]
	v_mfma_f32_16x16x32_bf16 v[60:63], v[132:135], v[190:193], v[60:63]
	v_mfma_f32_16x16x32_bf16 v[56:59], v[140:143], v[190:193], v[56:59]
	v_mfma_f32_16x16x32_bf16 v[44:47], v[132:135], v[198:201], v[44:47]
	v_mfma_f32_16x16x32_bf16 v[40:43], v[140:143], v[198:201], v[40:43]
	v_mfma_f32_16x16x32_bf16 v[28:31], v[132:135], v[206:209], v[28:31]
	v_mfma_f32_16x16x32_bf16 v[24:27], v[140:143], v[206:209], v[24:27]
	v_mfma_f32_16x16x32_bf16 v[12:15], v[132:135], v[214:217], v[12:15]
	v_mfma_f32_16x16x32_bf16 v[8:11], v[140:143], v[214:217], v[8:11]
	v_mfma_f32_16x16x32_bf16 v[52:55], v[162:165], v[186:189], v[52:55]
	v_mfma_f32_16x16x32_bf16 v[48:51], v[170:173], v[186:189], v[48:51]
	v_mfma_f32_16x16x32_bf16 v[36:39], v[162:165], v[194:197], v[36:39]
	v_mfma_f32_16x16x32_bf16 v[32:35], v[170:173], v[194:197], v[32:35]
	v_mfma_f32_16x16x32_bf16 v[20:23], v[162:165], v[202:205], v[20:23]
	v_mfma_f32_16x16x32_bf16 v[16:19], v[170:173], v[202:205], v[16:19]
	v_mfma_f32_16x16x32_bf16 v[4:7], v[162:165], v[210:213], v[4:7]
	v_mfma_f32_16x16x32_bf16 v[0:3], v[170:173], v[210:213], v[0:3]
	v_mfma_f32_16x16x32_bf16 v[52:55], v[166:169], v[190:193], v[52:55]
	v_mfma_f32_16x16x32_bf16 v[48:51], v[180:183], v[190:193], v[48:51]
	v_mfma_f32_16x16x32_bf16 v[36:39], v[166:169], v[198:201], v[36:39]
	v_mfma_f32_16x16x32_bf16 v[32:35], v[180:183], v[198:201], v[32:35]
	v_mfma_f32_16x16x32_bf16 v[20:23], v[166:169], v[206:209], v[20:23]
	v_mfma_f32_16x16x32_bf16 v[16:19], v[180:183], v[206:209], v[16:19]
	v_mfma_f32_16x16x32_bf16 v[4:7], v[166:169], v[214:217], v[4:7]
	v_mfma_f32_16x16x32_bf16 v[0:3], v[180:183], v[214:217], v[0:3]
	s_barrier
	s_setprio 0
	s_add_i32 s56, s56, 2
	s_add_u32 s34, s34, 0x100
	s_addc_u32 s35, s35, 0
	s_add_u32 s54, s54, 0x100
	s_addc_u32 s55, s55, 0
	s_cmp_gt_u32 s56, 13
	s_cbranch_scc0 .LBB0_1007
	s_and_b64 vcc, exec, s[16:17]
	s_cbranch_vccz .LBB0_1010
	s_barrier

; #define PG8_STAGE(bufoff, gbase, voff) do { _Pragma("unroll") for (int _i = 0; _i < 2; ++_i) \
;         __builtin_amdgcn_global_load_lds((const unsigned*)((const char*)(gbase) + (voff)[_i]), (PG8_LAS unsigned*)(lds + (bufoff) + ldsw + _i * 8192), 16, 0, 0); } while (0)
; #define PG8_LDA(dst, b, h) do { _Pragma("unroll") for (int m = 0; m < 4; ++m) _Pragma("unroll") for (int k = 0; k < 2; ++k) dst[m][k] = *(const PG8_LAS bf16x8*)(lds + PG8_SA(b, h) + aoff + m * 2048 + k * 1024); } while (0)
; #define PG8_LDB(dst, b, h) do { _Pragma("unroll") for (int n = 0; n < 2; ++n) _Pragma("unroll") for (int k = 0; k < 2; ++k) dst[n][k] = *(const PG8_LAS bf16x8*)(lds + PG8_SB(b, h) + boff + n * 2048 + k * 1024); } while (0)
; #define PG8_MMA(ai, bj, At, Bt) do { __builtin_amdgcn_s_setprio(1); _Pragma("unroll") for (int m = 0; m < 4; ++m) _Pragma("unroll") for (int n = 0; n < 2; ++n) _Pragma("unroll") for (int k = 0; k < 2; ++k) \
;         acc[ai][bj][m][n] = __builtin_amdgcn_mfma_f32_16x16x32_bf16(Bt[n][k], At[m][k], acc[ai][bj][m][n], 0, 0, 0); __builtin_amdgcn_s_setprio(0); } while (0)
; #define PG8_WAIT_V(n) asm volatile("s_waitcnt vmcnt(" #n ")" ::: "memory")
; #define PG8_WAIT_L(n) asm volatile("s_waitcnt lgkmcnt(" #n ")" ::: "memory")
; #define PG8_BAR __builtin_amdgcn_s_barrier()
; #define PG8_SCHED __builtin_amdgcn_sched_barrier(0)
; template <class Epi, class Sched, bool ALIGN_EPI = false, bool SP2 = false>
; __device__ __forceinline__ void gemm_phase(PG8_LAS unsigned char* lds, const Gemm g, const Sched& S, const Epi& E) {
;     ...
;             PG8_LDB(B0, 0, 0); PG8_LDB(B1, 0, 1); PG8_SCHED; PG8_LDA(At, 0, 0); PG8_STAGE(PG8_SA(1, 1), a1 + hstepA, voffA);
;             PG8_WAIT_V(8); PG8_WAIT_L(0); PG8_BAR; PG8_MMA(0, 0, At, B0); PG8_MMA(0, 1, At, B1); PG8_BAR; PG8_SCHED;
;             PG8_LDA(At, 0, 1); PG8_STAGE(PG8_SB(0, 0), b2, voffB); PG8_STAGE(PG8_SB(0, 1), b2 + hstepB, voffB); PG8_STAGE(PG8_SA(0, 0), a2, voffA);
.LBB0_1061:
	ds_read_b128 v[128:131], v199
	ds_read_b128 v[132:135], v199 offset:1024
	ds_read_b128 v[136:139], v199 offset:2048
	ds_read_b128 v[140:143], v199 offset:3072
	ds_read_b128 v[144:147], v200
	ds_read_b128 v[148:151], v200 offset:1024
	ds_read_b128 v[152:155], v200 offset:2048
	ds_read_b128 v[156:159], v200 offset:3072
	s_add_u32 s20, s18, 0xfff00080
	s_addc_u32 s21, s19, -1
	s_cmp_eq_u32 s45, 60
	s_cselect_b32 s23, s11, s21
	s_cselect_b32 s22, s41, s20
	s_cselect_b32 s21, s9, s44
	s_cselect_b32 s20, s42, s43
	v_lshl_add_u64 v[196:197], s[18:19], 0, v[180:181]
	s_add_i32 m0, s17, 0xc000
	ds_read_b128 v[160:163], v201
	ds_read_b128 v[164:167], v201 offset:1024
	ds_read_b128 v[188:191], v201 offset:2048
	ds_read_b128 v[192:195], v201 offset:3072
	ds_read_b128 v[202:205], v201 offset:4096
	ds_read_b128 v[206:209], v201 offset:5120
	ds_read_b128 v[210:213], v201 offset:6144
	ds_read_b128 v[214:217], v201 offset:7168
	global_load_lds_dwordx4 v[196:197], off
	v_lshl_add_u64 v[196:197], s[18:19], 0, v[182:183]
	s_add_i32 m0, s17, 0xe000
	s_nop 0
	global_load_lds_dwordx4 v[196:197], off
	s_waitcnt vmcnt(8) lgkmcnt(0)
	s_setprio 1
	s_barrier
	v_mfma_f32_16x16x32_bf16 v[124:127], v[128:131], v[160:163], v[124:127]
	v_mfma_f32_16x16x32_bf16 v[120:123], v[136:139], v[160:163], v[120:123]
	v_mfma_f32_16x16x32_bf16 v[112:115], v[128:131], v[188:191], v[112:115]
	v_mfma_f32_16x16x32_bf16 v[104:107], v[136:139], v[188:191], v[104:107]
	v_mfma_f32_16x16x32_bf16 v[96:99], v[128:131], v[202:205], v[96:99]
	v_mfma_f32_16x16x32_bf16 v[88:91], v[136:139], v[202:205], v[88:91]
	v_mfma_f32_16x16x32_bf16 v[80:83], v[128:131], v[210:213], v[80:83]
	v_mfma_f32_16x16x32_bf16 v[72:75], v[136:139], v[210:213], v[72:75]
	v_mfma_f32_16x16x32_bf16 v[124:127], v[132:135], v[164:167], v[124:127]
	v_mfma_f32_16x16x32_bf16 v[120:123], v[140:143], v[164:167], v[120:123]
	v_mfma_f32_16x16x32_bf16 v[112:115], v[132:135], v[192:195], v[112:115]
	v_mfma_f32_16x16x32_bf16 v[104:107], v[140:143], v[192:195], v[104:107]
	v_mfma_f32_16x16x32_bf16 v[96:99], v[132:135], v[206:209], v[96:99]
	v_mfma_f32_16x16x32_bf16 v[88:91], v[140:143], v[206:209], v[88:91]
	v_mfma_f32_16x16x32_bf16 v[80:83], v[132:135], v[214:217], v[80:83]
	v_mfma_f32_16x16x32_bf16 v[72:75], v[140:143], v[214:217], v[72:75]
	v_mfma_f32_16x16x32_bf16 v[116:119], v[144:147], v[160:163], v[116:119]
	v_mfma_f32_16x16x32_bf16 v[108:111], v[152:155], v[160:163], v[108:111]
	v_mfma_f32_16x16x32_bf16 v[100:103], v[144:147], v[188:191], v[100:103]
	v_mfma_f32_16x16x32_bf16 v[92:95], v[152:155], v[188:191], v[92:95]
	v_mfma_f32_16x16x32_bf16 v[84:87], v[144:147], v[202:205], v[84:87]
	v_mfma_f32_16x16x32_bf16 v[76:79], v[152:155], v[202:205], v[76:79]
	v_mfma_f32_16x16x32_bf16 v[68:71], v[144:147], v[210:213], v[68:71]
	v_mfma_f32_16x16x32_bf16 v[64:67], v[152:155], v[210:213], v[64:67]
	v_mfma_f32_16x16x32_bf16 v[116:119], v[148:151], v[164:167], v[116:119]
	v_mfma_f32_16x16x32_bf16 v[108:111], v[156:159], v[164:167], v[108:111]
	v_mfma_f32_16x16x32_bf16 v[100:103], v[148:151], v[192:195], v[100:103]
	v_mfma_f32_16x16x32_bf16 v[92:95], v[156:159], v[192:195], v[92:95]
	v_mfma_f32_16x16x32_bf16 v[84:87], v[148:151], v[206:209], v[84:87]
	v_mfma_f32_16x16x32_bf16 v[76:79], v[156:159], v[206:209], v[76:79]
	v_mfma_f32_16x16x32_bf16 v[68:71], v[148:151], v[214:217], v[68:71]
	v_mfma_f32_16x16x32_bf16 v[64:67], v[156:159], v[214:217], v[64:67]
	s_barrier
	s_setprio 0
	s_add_i32 s46, s38, s29
	v_lshl_add_u64 v[196:197], s[20:21], 0, v[170:171]
	s_mov_b32 m0, s46
	ds_read_b128 v[160:163], v201 offset:16384
	ds_read_b128 v[164:167], v201 offset:17408
	ds_read_b128 v[188:191], v201 offset:18432
	ds_read_b128 v[192:195], v201 offset:19456
	ds_read_b128 v[202:205], v201 offset:20480
	ds_read_b128 v[206:209], v201 offset:21504
	ds_read_b128 v[210:213], v201 offset:22528
	ds_read_b128 v[214:217], v201 offset:23552
	global_load_lds_dwordx4 v[196:197], off
	s_add_i32 m0, s46, 0x2000
	s_add_u32 s46, s20, 0x100000
	v_lshl_add_u64 v[218:219], s[20:21], 0, v[174:175]
	s_addc_u32 s47, s21, 0
	s_add_i32 s48, s39, s29
	global_load_lds_dwordx4 v[218:219], off
	v_lshl_add_u64 v[220:221], s[46:47], 0, v[170:171]
	s_mov_b32 m0, s48
	v_lshl_add_u64 v[222:223], s[22:23], 0, v[172:173]
	global_load_lds_dwordx4 v[220:221], off
	v_lshl_add_u64 v[220:221], s[46:47], 0, v[174:175]
	s_add_i32 m0, s48, 0x2000
	s_nop 0
	global_load_lds_dwordx4 v[220:221], off
	v_lshl_add_u64 v[220:221], s[22:23], 0, v[168:169]
	s_mov_b32 m0, s17
	s_nop 0
	global_load_lds_dwordx4 v[220:221], off
	s_mov_b32 m0, s30
	s_nop 0
	global_load_lds_dwordx4 v[222:223], off
	s_waitcnt vmcnt(8) lgkmcnt(0)
	s_setprio 1
	s_barrier
; #define PG8_STAGE(bufoff, gbase, voff) do { _Pragma("unroll") for (int _i = 0; _i < 2; ++_i) \
;         __builtin_amdgcn_global_load_lds((const unsigned*)((const char*)(gbase) + (voff)[_i]), (PG8_LAS unsigned*)(lds + (bufoff) + ldsw + _i * 8192), 16, 0, 0); } while (0)
; #define PG8_LDA(dst, b, h) do { _Pragma("unroll") for (int m = 0; m < 4; ++m) _Pragma("unroll") for (int k = 0; k < 2; ++k) dst[m][k] = *(const PG8_LAS bf16x8*)(lds + PG8_SA(b, h) + aoff + m * 2048 + k * 1024); } while (0)
; #define PG8_LDB(dst, b, h) do { _Pragma("unroll") for (int n = 0; n < 2; ++n) _Pragma("unroll") for (int k = 0; k < 2; ++k) dst[n][k] = *(const PG8_LAS bf16x8*)(lds + PG8_SB(b, h) + boff + n * 2048 + k * 1024); } while (0)
; #define PG8_MMA(ai, bj, At, Bt) do { __builtin_amdgcn_s_setprio(1); _Pragma("unroll") for (int m = 0; m < 4; ++m) _Pragma("unroll") for (int n = 0; n < 2; ++n) _Pragma("unroll") for (int k = 0; k < 2; ++k) \
;         acc[ai][bj][m][n] = __builtin_amdgcn_mfma_f32_16x16x32_bf16(Bt[n][k], At[m][k], acc[ai][bj][m][n], 0, 0, 0); __builtin_amdgcn_s_setprio(0); } while (0)
; #define PG8_WAIT_V(n) asm volatile("s_waitcnt vmcnt(" #n ")" ::: "memory")
; #define PG8_WAIT_L(n) asm volatile("s_waitcnt lgkmcnt(" #n ")" ::: "memory")
; #define PG8_BAR __builtin_amdgcn_s_barrier()
; #define PG8_SCHED __builtin_amdgcn_sched_barrier(0)
; template <class Epi, class Sched, bool ALIGN_EPI = false, bool SP2 = false>
; __device__ __forceinline__ void gemm_phase(PG8_LAS unsigned char* lds, const Gemm g, const Sched& S, const Epi& E) {
;     ...
;             PG8_WAIT_V(8); PG8_WAIT_L(0); PG8_BAR; PG8_MMA(1, 0, At, B0); PG8_MMA(1, 1, At, B1); PG8_BAR; PG8_SCHED;
;             PG8_LDB(B0, 1, 0); PG8_LDB(B1, 1, 1); PG8_SCHED; PG8_LDA(At, 1, 0); PG8_STAGE(PG8_SA(0, 1), a2 + hstepA, voffA);
;             PG8_WAIT_V(8); PG8_WAIT_L(0); PG8_BAR; PG8_MMA(0, 0, At, B0); PG8_MMA(0, 1, At, B1); PG8_BAR; PG8_SCHED;
	v_mfma_f32_16x16x32_bf16 v[60:63], v[128:131], v[160:163], v[60:63]
	v_mfma_f32_16x16x32_bf16 v[56:59], v[136:139], v[160:163], v[56:59]
	v_mfma_f32_16x16x32_bf16 v[48:51], v[128:131], v[188:191], v[48:51]
	v_mfma_f32_16x16x32_bf16 v[40:43], v[136:139], v[188:191], v[40:43]
	v_mfma_f32_16x16x32_bf16 v[32:35], v[128:131], v[202:205], v[32:35]
	v_mfma_f32_16x16x32_bf16 v[24:27], v[136:139], v[202:205], v[24:27]
	v_mfma_f32_16x16x32_bf16 v[16:19], v[128:131], v[210:213], v[16:19]
	v_mfma_f32_16x16x32_bf16 v[8:11], v[136:139], v[210:213], v[8:11]
	v_mfma_f32_16x16x32_bf16 v[60:63], v[132:135], v[164:167], v[60:63]
	v_mfma_f32_16x16x32_bf16 v[56:59], v[140:143], v[164:167], v[56:59]
	v_mfma_f32_16x16x32_bf16 v[48:51], v[132:135], v[192:195], v[48:51]
	v_mfma_f32_16x16x32_bf16 v[40:43], v[140:143], v[192:195], v[40:43]
	v_mfma_f32_16x16x32_bf16 v[32:35], v[132:135], v[206:209], v[32:35]
	v_mfma_f32_16x16x32_bf16 v[24:27], v[140:143], v[206:209], v[24:27]
	v_mfma_f32_16x16x32_bf16 v[16:19], v[132:135], v[214:217], v[16:19]
	v_mfma_f32_16x16x32_bf16 v[8:11], v[140:143], v[214:217], v[8:11]
	v_mfma_f32_16x16x32_bf16 v[52:55], v[144:147], v[160:163], v[52:55]
	v_mfma_f32_16x16x32_bf16 v[44:47], v[152:155], v[160:163], v[44:47]
	v_mfma_f32_16x16x32_bf16 v[36:39], v[144:147], v[188:191], v[36:39]
	v_mfma_f32_16x16x32_bf16 v[28:31], v[152:155], v[188:191], v[28:31]
	v_mfma_f32_16x16x32_bf16 v[20:23], v[144:147], v[202:205], v[20:23]
	v_mfma_f32_16x16x32_bf16 v[12:15], v[152:155], v[202:205], v[12:15]
	v_mfma_f32_16x16x32_bf16 v[4:7], v[144:147], v[210:213], v[4:7]
	v_mfma_f32_16x16x32_bf16 v[0:3], v[152:155], v[210:213], v[0:3]
	v_mfma_f32_16x16x32_bf16 v[52:55], v[148:151], v[164:167], v[52:55]
	v_mfma_f32_16x16x32_bf16 v[44:47], v[156:159], v[164:167], v[44:47]
	v_mfma_f32_16x16x32_bf16 v[36:39], v[148:151], v[192:195], v[36:39]
	v_mfma_f32_16x16x32_bf16 v[28:31], v[156:159], v[192:195], v[28:31]
	v_mfma_f32_16x16x32_bf16 v[20:23], v[148:151], v[206:209], v[20:23]
	v_mfma_f32_16x16x32_bf16 v[12:15], v[156:159], v[206:209], v[12:15]
	v_mfma_f32_16x16x32_bf16 v[4:7], v[148:151], v[214:217], v[4:7]
	v_mfma_f32_16x16x32_bf16 v[0:3], v[156:159], v[214:217], v[0:3]
	s_barrier
	s_setprio 0
	s_add_i32 s46, 0, 0x18000
	s_add_i32 s47, 0, 0x1c000
	v_add_u32_e32 v140, s46, v198
	v_add_u32_e32 v156, s47, v198
	ds_read_b128 v[128:131], v140
	ds_read_b128 v[132:135], v140 offset:1024
	ds_read_b128 v[136:139], v140 offset:2048
	ds_read_b128 v[140:143], v140 offset:3072
	ds_read_b128 v[144:147], v156
	ds_read_b128 v[148:151], v156 offset:1024
	ds_read_b128 v[152:155], v156 offset:2048
	ds_read_b128 v[156:159], v156 offset:3072
	s_add_u32 s22, s22, 0x100000
	s_addc_u32 s23, s23, 0
	s_mov_b32 m0, s31
	v_lshl_add_u64 v[224:225], s[22:23], 0, v[168:169]
	ds_read_b128 v[160:163], v201 offset:32768
	ds_read_b128 v[164:167], v201 offset:33792
	ds_read_b128 v[188:191], v201 offset:34816
	ds_read_b128 v[192:195], v201 offset:35840
	ds_read_b128 v[202:205], v201 offset:36864
	ds_read_b128 v[206:209], v201 offset:37888
	ds_read_b128 v[210:213], v201 offset:38912
	ds_read_b128 v[214:217], v201 offset:39936
	global_load_lds_dwordx4 v[224:225], off
	v_lshl_add_u64 v[224:225], s[22:23], 0, v[172:173]
	s_mov_b32 m0, s33
	s_nop 0
	global_load_lds_dwordx4 v[224:225], off
	s_waitcnt vmcnt(8) lgkmcnt(0)
	s_setprio 1
	s_barrier
	v_mfma_f32_16x16x32_bf16 v[124:127], v[128:131], v[160:163], v[124:127]
	v_mfma_f32_16x16x32_bf16 v[120:123], v[136:139], v[160:163], v[120:123]
	v_mfma_f32_16x16x32_bf16 v[112:115], v[128:131], v[188:191], v[112:115]
	v_mfma_f32_16x16x32_bf16 v[104:107], v[136:139], v[188:191], v[104:107]
	v_mfma_f32_16x16x32_bf16 v[96:99], v[128:131], v[202:205], v[96:99]
	v_mfma_f32_16x16x32_bf16 v[88:91], v[136:139], v[202:205], v[88:91]
	v_mfma_f32_16x16x32_bf16 v[80:83], v[128:131], v[210:213], v[80:83]
	v_mfma_f32_16x16x32_bf16 v[72:75], v[136:139], v[210:213], v[72:75]
	v_mfma_f32_16x16x32_bf16 v[124:127], v[132:135], v[164:167], v[124:127]
	v_mfma_f32_16x16x32_bf16 v[120:123], v[140:143], v[164:167], v[120:123]
	v_mfma_f32_16x16x32_bf16 v[112:115], v[132:135], v[192:195], v[112:115]
	v_mfma_f32_16x16x32_bf16 v[104:107], v[140:143], v[192:195], v[104:107]
	v_mfma_f32_16x16x32_bf16 v[96:99], v[132:135], v[206:209], v[96:99]
	v_mfma_f32_16x16x32_bf16 v[88:91], v[140:143], v[206:209], v[88:91]
	v_mfma_f32_16x16x32_bf16 v[80:83], v[132:135], v[214:217], v[80:83]
	v_mfma_f32_16x16x32_bf16 v[72:75], v[140:143], v[214:217], v[72:75]
	v_mfma_f32_16x16x32_bf16 v[116:119], v[144:147], v[160:163], v[116:119]
	v_mfma_f32_16x16x32_bf16 v[108:111], v[152:155], v[160:163], v[108:111]
	v_mfma_f32_16x16x32_bf16 v[100:103], v[144:147], v[188:191], v[100:103]
	v_mfma_f32_16x16x32_bf16 v[92:95], v[152:155], v[188:191], v[92:95]
	v_mfma_f32_16x16x32_bf16 v[84:87], v[144:147], v[202:205], v[84:87]
	v_mfma_f32_16x16x32_bf16 v[76:79], v[152:155], v[202:205], v[76:79]
	v_mfma_f32_16x16x32_bf16 v[68:71], v[144:147], v[210:213], v[68:71]
	v_mfma_f32_16x16x32_bf16 v[64:67], v[152:155], v[210:213], v[64:67]
	v_mfma_f32_16x16x32_bf16 v[116:119], v[148:151], v[164:167], v[116:119]
	v_mfma_f32_16x16x32_bf16 v[108:111], v[156:159], v[164:167], v[108:111]
	v_mfma_f32_16x16x32_bf16 v[100:103], v[148:151], v[192:195], v[100:103]
	v_mfma_f32_16x16x32_bf16 v[92:95], v[156:159], v[192:195], v[92:95]
	v_mfma_f32_16x16x32_bf16 v[84:87], v[148:151], v[206:209], v[84:87]
	v_mfma_f32_16x16x32_bf16 v[76:79], v[156:159], v[206:209], v[76:79]
	v_mfma_f32_16x16x32_bf16 v[68:71], v[148:151], v[214:217], v[68:71]
	v_mfma_f32_16x16x32_bf16 v[64:67], v[156:159], v[214:217], v[64:67]
	s_barrier
; #define PG8_STAGE(bufoff, gbase, voff) do { _Pragma("unroll") for (int _i = 0; _i < 2; ++_i) \
;         __builtin_amdgcn_global_load_lds((const unsigned*)((const char*)(gbase) + (voff)[_i]), (PG8_LAS unsigned*)(lds + (bufoff) + ldsw + _i * 8192), 16, 0, 0); } while (0)
; #define PG8_LDA(dst, b, h) do { _Pragma("unroll") for (int m = 0; m < 4; ++m) _Pragma("unroll") for (int k = 0; k < 2; ++k) dst[m][k] = *(const PG8_LAS bf16x8*)(lds + PG8_SA(b, h) + aoff + m * 2048 + k * 1024); } while (0)
; #define PG8_MMA(ai, bj, At, Bt) do { __builtin_amdgcn_s_setprio(1); _Pragma("unroll") for (int m = 0; m < 4; ++m) _Pragma("unroll") for (int n = 0; n < 2; ++n) _Pragma("unroll") for (int k = 0; k < 2; ++k) \
;         acc[ai][bj][m][n] = __builtin_amdgcn_mfma_f32_16x16x32_bf16(Bt[n][k], At[m][k], acc[ai][bj][m][n], 0, 0, 0); __builtin_amdgcn_s_setprio(0); } while (0)
; #define PG8_WAIT_V(n) asm volatile("s_waitcnt vmcnt(" #n ")" ::: "memory")
; #define PG8_WAIT_L(n) asm volatile("s_waitcnt lgkmcnt(" #n ")" ::: "memory")
; #define PG8_BAR __builtin_amdgcn_s_barrier()
; #define PG8_SCHED __builtin_amdgcn_sched_barrier(0)
; template <class Epi, class Sched, bool ALIGN_EPI = false, bool SP2 = false>
; __device__ __forceinline__ void gemm_phase(PG8_LAS unsigned char* lds, const Gemm g, const Sched& S, const Epi& E) {
;     ...
;             PG8_LDA(At, 1, 1); PG8_STAGE(PG8_SB(1, 0), b3, voffB); PG8_STAGE(PG8_SB(1, 1), b3 + hstepB, voffB); PG8_STAGE(PG8_SA(1, 0), a3, voffA);
;             PG8_WAIT_V(8); PG8_WAIT_L(0); PG8_BAR; PG8_MMA(1, 0, At, B0); PG8_MMA(1, 1, At, B1); PG8_BAR; PG8_SCHED;
;     ...
;         if constexpr (ALIGN_EPI) { if (wr == 0) PG8_BAR; }
	s_setprio 0
	s_add_i32 s22, s46, s29
	v_lshl_add_u64 v[196:197], v[196:197], 0, s[4:5]
	s_mov_b32 m0, s22
	ds_read_b128 v[160:163], v201 offset:49152
	ds_read_b128 v[164:167], v201 offset:50176
	ds_read_b128 v[188:191], v201 offset:51200
	ds_read_b128 v[192:195], v201 offset:52224
	ds_read_b128 v[202:205], v201 offset:53248
	ds_read_b128 v[206:209], v201 offset:54272
	ds_read_b128 v[210:213], v201 offset:55296
	ds_read_b128 v[214:217], v201 offset:56320
	global_load_lds_dwordx4 v[196:197], off
	s_add_i32 m0, s22, 0x2000
	s_add_u32 s20, s20, 0x100080
	v_lshl_add_u64 v[196:197], v[218:219], 0, s[4:5]
	s_addc_u32 s21, s21, 0
	s_add_i32 s22, s47, s29
	global_load_lds_dwordx4 v[196:197], off
	v_lshl_add_u64 v[196:197], s[20:21], 0, v[170:171]
	s_mov_b32 m0, s22
	s_nop 0
	global_load_lds_dwordx4 v[196:197], off
	v_lshl_add_u64 v[196:197], s[20:21], 0, v[174:175]
	s_add_i32 m0, s22, 0x2000
	s_nop 0
	global_load_lds_dwordx4 v[196:197], off
	v_lshl_add_u64 v[196:197], v[220:221], 0, s[4:5]
	s_mov_b32 m0, s35
	s_nop 0
	global_load_lds_dwordx4 v[196:197], off
	v_lshl_add_u64 v[196:197], v[222:223], 0, s[4:5]
	s_mov_b32 m0, s36
	s_nop 0
	global_load_lds_dwordx4 v[196:197], off
	s_waitcnt vmcnt(8) lgkmcnt(0)
	s_setprio 1
	s_barrier
	v_mfma_f32_16x16x32_bf16 v[60:63], v[128:131], v[160:163], v[60:63]
	v_mfma_f32_16x16x32_bf16 v[56:59], v[136:139], v[160:163], v[56:59]
	v_mfma_f32_16x16x32_bf16 v[48:51], v[128:131], v[188:191], v[48:51]
	v_mfma_f32_16x16x32_bf16 v[40:43], v[136:139], v[188:191], v[40:43]
	v_mfma_f32_16x16x32_bf16 v[32:35], v[128:131], v[202:205], v[32:35]
	v_mfma_f32_16x16x32_bf16 v[24:27], v[136:139], v[202:205], v[24:27]
	v_mfma_f32_16x16x32_bf16 v[16:19], v[128:131], v[210:213], v[16:19]
	v_mfma_f32_16x16x32_bf16 v[8:11], v[136:139], v[210:213], v[8:11]
	v_mfma_f32_16x16x32_bf16 v[60:63], v[132:135], v[164:167], v[60:63]
	v_mfma_f32_16x16x32_bf16 v[56:59], v[140:143], v[164:167], v[56:59]
	v_mfma_f32_16x16x32_bf16 v[48:51], v[132:135], v[192:195], v[48:51]
	v_mfma_f32_16x16x32_bf16 v[40:43], v[140:143], v[192:195], v[40:43]
	v_mfma_f32_16x16x32_bf16 v[32:35], v[132:135], v[206:209], v[32:35]
	v_mfma_f32_16x16x32_bf16 v[24:27], v[140:143], v[206:209], v[24:27]
	v_mfma_f32_16x16x32_bf16 v[16:19], v[132:135], v[214:217], v[16:19]
	v_mfma_f32_16x16x32_bf16 v[8:11], v[140:143], v[214:217], v[8:11]
	v_mfma_f32_16x16x32_bf16 v[52:55], v[144:147], v[160:163], v[52:55]
	v_mfma_f32_16x16x32_bf16 v[44:47], v[152:155], v[160:163], v[44:47]
	v_mfma_f32_16x16x32_bf16 v[36:39], v[144:147], v[188:191], v[36:39]
	v_mfma_f32_16x16x32_bf16 v[28:31], v[152:155], v[188:191], v[28:31]
	v_mfma_f32_16x16x32_bf16 v[20:23], v[144:147], v[202:205], v[20:23]
	v_mfma_f32_16x16x32_bf16 v[12:15], v[152:155], v[202:205], v[12:15]
	v_mfma_f32_16x16x32_bf16 v[4:7], v[144:147], v[210:213], v[4:7]
	v_mfma_f32_16x16x32_bf16 v[0:3], v[152:155], v[210:213], v[0:3]
	v_mfma_f32_16x16x32_bf16 v[52:55], v[148:151], v[164:167], v[52:55]
	v_mfma_f32_16x16x32_bf16 v[44:47], v[156:159], v[164:167], v[44:47]
	v_mfma_f32_16x16x32_bf16 v[36:39], v[148:151], v[192:195], v[36:39]
	v_mfma_f32_16x16x32_bf16 v[28:31], v[156:159], v[192:195], v[28:31]
	v_mfma_f32_16x16x32_bf16 v[20:23], v[148:151], v[206:209], v[20:23]
	v_mfma_f32_16x16x32_bf16 v[12:15], v[156:159], v[206:209], v[12:15]
	v_mfma_f32_16x16x32_bf16 v[4:7], v[148:151], v[214:217], v[4:7]
	v_mfma_f32_16x16x32_bf16 v[0:3], v[156:159], v[214:217], v[0:3]
	s_barrier
	s_setprio 0
	s_add_i32 s45, s45, 2
	s_add_u32 s18, s18, 0x100
	s_addc_u32 s19, s19, 0
	s_add_u32 s43, s43, 0x100
	s_addc_u32 s44, s44, 0
	s_cmp_gt_u32 s45, 61
	s_cbranch_scc0 .LBB0_1061
	s_and_b64 vcc, exec, s[6:7]
	s_cbranch_vccz .LBB0_1064
	s_barrier
